# SwiGLU rstd partials via LDS-DMA copy of SS tile + 64-bit accumulator zeroing
# speedup vs baseline: 1.0106x; 1.0106x over previous
; template <class Epi>
; __device__ __forceinline__ void gemm_phase(LAS unsigned char* lds, const Gemm g, const StaticOrder& S, const Epi& E, const int tid) {
;     ...
;         const bool has_next = S.next(ui + 1, nxt);
;         const char* nA = has_next ? (const char*)g.A + (size_t)nxt.pm * tstepA + (size_t)nxt.pn * pnoffA : cA; const char* nB = has_next ? (const char*)g.Bt + (size_t)nxt.pn * tstepB : cB;
;     ...
; #pragma unroll
;         for (int a = 0; a < 2; ++a)
; #pragma unroll
;             for (int b = 0; b < 2; ++b)
; #pragma unroll
;                 for (int m = 0; m < 4; ++m)
; #pragma unroll
;                     for (int n = 0; n < 2; ++n) acc[a][b][m][n] = (f32x4){0.f, 0.f, 0.f, 0.f};
.LBB0_224:
	s_ashr_i32 s11, s10, 31
	s_lshl_b64 s[12:13], s[10:11], 19
	s_add_u32 s12, s24, s12
	s_addc_u32 s13, s25, s13
	s_and_b64 s[14:15], s[4:5], exec
	s_cselect_b32 s11, s13, s17
	s_cselect_b32 s47, s12, s16
	s_ashr_i32 s9, s8, 31
	s_lshl_b64 s[14:15], s[8:9], 19
	s_add_u32 s14, s84, s14
	s_addc_u32 s15, s85, s15
	s_and_b64 s[34:35], s[4:5], exec
	s_cselect_b32 s9, s15, s29
	s_cselect_b32 s48, s14, s28
	s_add_u32 s49, s28, 0x100
	v_mov_b32_e32 v0, 0
	s_addc_u32 s50, s29, 0
	s_mov_b32 s51, -2
	v_mov_b64_e32 v[0:1], 0
	v_mov_b64_e32 v[2:3], 0
	v_mov_b64_e32 v[4:5], 0
	v_mov_b64_e32 v[6:7], 0
	v_mov_b64_e32 v[8:9], 0
	v_mov_b64_e32 v[10:11], 0
	v_mov_b64_e32 v[12:13], 0
	v_mov_b64_e32 v[14:15], 0
	v_mov_b64_e32 v[16:17], 0
	v_mov_b64_e32 v[18:19], 0
	v_mov_b64_e32 v[20:21], 0
	v_mov_b64_e32 v[22:23], 0
	v_mov_b64_e32 v[24:25], 0
	v_mov_b64_e32 v[26:27], 0
	v_mov_b64_e32 v[28:29], 0
	v_mov_b64_e32 v[30:31], 0
	v_mov_b64_e32 v[32:33], 0
	v_mov_b64_e32 v[34:35], 0
	v_mov_b64_e32 v[36:37], 0
	v_mov_b64_e32 v[38:39], 0
	v_mov_b64_e32 v[40:41], 0
	v_mov_b64_e32 v[42:43], 0
	v_mov_b64_e32 v[44:45], 0
	v_mov_b64_e32 v[46:47], 0
	v_mov_b64_e32 v[48:49], 0
	v_mov_b64_e32 v[50:51], 0
	v_mov_b64_e32 v[52:53], 0
	v_mov_b64_e32 v[54:55], 0
	v_mov_b64_e32 v[56:57], 0
	v_mov_b64_e32 v[58:59], 0
	v_mov_b64_e32 v[60:61], 0
	v_mov_b64_e32 v[62:63], 0
	v_mov_b64_e32 v[64:65], 0
	v_mov_b64_e32 v[66:67], 0
	v_mov_b64_e32 v[68:69], 0
	v_mov_b64_e32 v[70:71], 0
	v_mov_b64_e32 v[72:73], 0
	v_mov_b64_e32 v[74:75], 0
	v_mov_b64_e32 v[76:77], 0
	v_mov_b64_e32 v[78:79], 0
	v_mov_b64_e32 v[80:81], 0
	v_mov_b64_e32 v[82:83], 0
	v_mov_b64_e32 v[84:85], 0
	v_mov_b64_e32 v[86:87], 0
	v_mov_b64_e32 v[88:89], 0
	v_mov_b64_e32 v[90:91], 0
	v_mov_b64_e32 v[92:93], 0
	v_mov_b64_e32 v[94:95], 0
	v_mov_b64_e32 v[96:97], 0
	v_mov_b64_e32 v[98:99], 0
	v_mov_b64_e32 v[100:101], 0
	v_mov_b64_e32 v[102:103], 0
	v_mov_b64_e32 v[104:105], 0
	v_mov_b64_e32 v[106:107], 0
	v_mov_b64_e32 v[108:109], 0
	v_mov_b64_e32 v[110:111], 0
	v_mov_b64_e32 v[112:113], 0
	v_mov_b64_e32 v[114:115], 0
	v_mov_b64_e32 v[116:117], 0
	v_mov_b64_e32 v[118:119], 0
	v_mov_b64_e32 v[120:121], 0
	v_mov_b64_e32 v[122:123], 0
	v_mov_b64_e32 v[124:125], 0
	v_mov_b64_e32 v[126:127], 0

; template <class Epi>
; __device__ __forceinline__ void gemm_phase(LAS unsigned char* lds, const Gemm g, const StaticOrder& S, const Epi& E, const int tid) {
;     ...
;         const bool has_next = S.next(ui + 1, nxt);
;         const char* nA = has_next ? (const char*)g.A + (size_t)nxt.pm * tstepA + (size_t)nxt.pn * pnoffA : cA; const char* nB = has_next ? (const char*)g.Bt + (size_t)nxt.pn * tstepB : cB;
;     ...
; #pragma unroll
;         for (int a = 0; a < 2; ++a)
; #pragma unroll
;             for (int b = 0; b < 2; ++b)
; #pragma unroll
;                 for (int m = 0; m < 4; ++m)
; #pragma unroll
;                     for (int n = 0; n < 2; ++n) acc[a][b][m][n] = (f32x4){0.f, 0.f, 0.f, 0.f};
.LBB0_338:
	s_ashr_i32 s15, s14, 31
	s_lshl_b64 s[2:3], s[14:15], 19
	s_add_u32 s16, s24, s2
	s_addc_u32 s17, s25, s3
	s_and_b64 s[2:3], s[4:5], exec
	s_cselect_b32 s15, s17, s29
	s_cselect_b32 s51, s16, s28
	s_ashr_i32 s13, s12, 31
	s_lshl_b64 s[2:3], s[12:13], 19
	s_add_u32 s2, s20, s2
	s_addc_u32 s3, s21, s3
	s_and_b64 s[40:41], s[4:5], exec
	s_cselect_b32 s13, s3, s35
	s_cselect_b32 s52, s2, s34
	s_add_u32 s53, s34, 0x100
	v_mov_b32_e32 v0, 0
	s_addc_u32 s54, s35, 0
	s_mov_b32 s55, -2
	v_mov_b64_e32 v[0:1], 0
	v_mov_b64_e32 v[2:3], 0
	v_mov_b64_e32 v[4:5], 0
	v_mov_b64_e32 v[6:7], 0
	v_mov_b64_e32 v[8:9], 0
	v_mov_b64_e32 v[10:11], 0
	v_mov_b64_e32 v[12:13], 0
	v_mov_b64_e32 v[14:15], 0
	v_mov_b64_e32 v[16:17], 0
	v_mov_b64_e32 v[18:19], 0
	v_mov_b64_e32 v[20:21], 0
	v_mov_b64_e32 v[22:23], 0
	v_mov_b64_e32 v[24:25], 0
	v_mov_b64_e32 v[26:27], 0
	v_mov_b64_e32 v[28:29], 0
	v_mov_b64_e32 v[30:31], 0
	v_mov_b64_e32 v[32:33], 0
	v_mov_b64_e32 v[34:35], 0
	v_mov_b64_e32 v[36:37], 0
	v_mov_b64_e32 v[38:39], 0
	v_mov_b64_e32 v[40:41], 0
	v_mov_b64_e32 v[42:43], 0
	v_mov_b64_e32 v[44:45], 0
	v_mov_b64_e32 v[46:47], 0
	v_mov_b64_e32 v[48:49], 0
	v_mov_b64_e32 v[50:51], 0
	v_mov_b64_e32 v[52:53], 0
	v_mov_b64_e32 v[54:55], 0
	v_mov_b64_e32 v[56:57], 0
	v_mov_b64_e32 v[58:59], 0
	v_mov_b64_e32 v[60:61], 0
	v_mov_b64_e32 v[62:63], 0
	v_mov_b64_e32 v[64:65], 0
	v_mov_b64_e32 v[66:67], 0
	v_mov_b64_e32 v[68:69], 0
	v_mov_b64_e32 v[70:71], 0
	v_mov_b64_e32 v[72:73], 0
	v_mov_b64_e32 v[74:75], 0
	v_mov_b64_e32 v[76:77], 0
	v_mov_b64_e32 v[78:79], 0
	v_mov_b64_e32 v[80:81], 0
	v_mov_b64_e32 v[82:83], 0
	v_mov_b64_e32 v[84:85], 0
	v_mov_b64_e32 v[86:87], 0
	v_mov_b64_e32 v[88:89], 0
	v_mov_b64_e32 v[90:91], 0
	v_mov_b64_e32 v[92:93], 0
	v_mov_b64_e32 v[94:95], 0
	v_mov_b64_e32 v[96:97], 0
	v_mov_b64_e32 v[98:99], 0
	v_mov_b64_e32 v[100:101], 0
	v_mov_b64_e32 v[102:103], 0
	v_mov_b64_e32 v[104:105], 0
	v_mov_b64_e32 v[106:107], 0
	v_mov_b64_e32 v[108:109], 0
	v_mov_b64_e32 v[110:111], 0
	v_mov_b64_e32 v[112:113], 0
	v_mov_b64_e32 v[114:115], 0
	v_mov_b64_e32 v[116:117], 0
	v_mov_b64_e32 v[118:119], 0
	v_mov_b64_e32 v[120:121], 0
	v_mov_b64_e32 v[122:123], 0
	v_mov_b64_e32 v[124:125], 0
	v_mov_b64_e32 v[126:127], 0

; template <class Epi>
; __device__ __forceinline__ void gemm_phase(LAS unsigned char* lds, const Gemm g, const StaticOrder& S, const Epi& E, const int tid) {
;     ...
; #pragma unroll
;         for (int a = 0; a < 2; ++a)
; #pragma unroll
;             for (int b = 0; b < 2; ++b)
; #pragma unroll
;                 for (int m = 0; m < 4; ++m)
; #pragma unroll
;                     for (int n = 0; n < 2; ++n) acc[a][b][m][n] = (f32x4){0.f, 0.f, 0.f, 0.f};
.LBB0_392:
	s_add_u32 s71, s2, s21
	s_addc_u32 s72, s3, 0
	s_add_u32 s73, s28, 0x100
	v_mov_b32_e32 v0, 0
	s_addc_u32 s75, s29, 0
	s_mov_b64 s[28:29], 0
	s_waitcnt lgkmcnt(0)
	v_mov_b64_e32 v[0:1], 0
	v_mov_b64_e32 v[2:3], 0
	v_mov_b64_e32 v[4:5], 0
	v_mov_b64_e32 v[6:7], 0
	v_mov_b64_e32 v[8:9], 0
	v_mov_b64_e32 v[10:11], 0
	v_mov_b64_e32 v[12:13], 0
	v_mov_b64_e32 v[14:15], 0
	v_mov_b64_e32 v[16:17], 0
	v_mov_b64_e32 v[18:19], 0
	v_mov_b64_e32 v[20:21], 0
	v_mov_b64_e32 v[22:23], 0
	v_mov_b64_e32 v[24:25], 0
	v_mov_b64_e32 v[26:27], 0
	v_mov_b64_e32 v[28:29], 0
	v_mov_b64_e32 v[30:31], 0
	v_mov_b64_e32 v[32:33], 0
	v_mov_b64_e32 v[34:35], 0
	v_mov_b64_e32 v[36:37], 0
	v_mov_b64_e32 v[38:39], 0
	v_mov_b64_e32 v[40:41], 0
	v_mov_b64_e32 v[42:43], 0
	v_mov_b64_e32 v[44:45], 0
	v_mov_b64_e32 v[46:47], 0
	v_mov_b64_e32 v[48:49], 0
	v_mov_b64_e32 v[50:51], 0
	v_mov_b64_e32 v[52:53], 0
	v_mov_b64_e32 v[54:55], 0
	v_mov_b64_e32 v[56:57], 0
	v_mov_b64_e32 v[58:59], 0
	v_mov_b64_e32 v[60:61], 0
	v_mov_b64_e32 v[62:63], 0
	v_mov_b64_e32 v[64:65], 0
	v_mov_b64_e32 v[66:67], 0
	v_mov_b64_e32 v[68:69], 0
	v_mov_b64_e32 v[70:71], 0
	v_mov_b64_e32 v[72:73], 0
	v_mov_b64_e32 v[74:75], 0
	v_mov_b64_e32 v[76:77], 0
	v_mov_b64_e32 v[78:79], 0
	v_mov_b64_e32 v[80:81], 0
	v_mov_b64_e32 v[82:83], 0
	v_mov_b64_e32 v[84:85], 0
	v_mov_b64_e32 v[86:87], 0
	v_mov_b64_e32 v[88:89], 0
	v_mov_b64_e32 v[90:91], 0
	v_mov_b64_e32 v[92:93], 0
	v_mov_b64_e32 v[94:95], 0
	v_mov_b64_e32 v[96:97], 0
	v_mov_b64_e32 v[98:99], 0
	v_mov_b64_e32 v[100:101], 0
	v_mov_b64_e32 v[102:103], 0
	v_mov_b64_e32 v[104:105], 0
	v_mov_b64_e32 v[106:107], 0
	v_mov_b64_e32 v[108:109], 0
	v_mov_b64_e32 v[110:111], 0
	v_mov_b64_e32 v[112:113], 0
	v_mov_b64_e32 v[114:115], 0
	v_mov_b64_e32 v[116:117], 0
	v_mov_b64_e32 v[118:119], 0
	v_mov_b64_e32 v[120:121], 0
	v_mov_b64_e32 v[122:123], 0
	v_mov_b64_e32 v[132:133], 0
	v_mov_b64_e32 v[134:135], 0

; template <class Epi>
; __device__ __forceinline__ void gemm_phase(LAS unsigned char* lds, const Gemm g, const StaticOrder& S, const Epi& E, const int tid) {
;     ...
; #pragma unroll
;         for (int a = 0; a < 2; ++a)
; #pragma unroll
;             for (int b = 0; b < 2; ++b)
; #pragma unroll
;                 for (int m = 0; m < 4; ++m)
; #pragma unroll
;                     for (int n = 0; n < 2; ++n) acc[a][b][m][n] = (f32x4){0.f, 0.f, 0.f, 0.f};
.LBB0_434:
	s_add_u32 s59, s2, 0x100
	s_addc_u32 s60, s3, 0
	s_add_u32 s2, s44, 0x800
	v_mov_b32_e32 v0, 0
	s_addc_u32 s3, s45, 0
	s_mov_b32 s44, 0
	v_mov_b64_e32 v[0:1], 0
	v_mov_b64_e32 v[2:3], 0
	v_mov_b64_e32 v[4:5], 0
	v_mov_b64_e32 v[6:7], 0
	v_mov_b64_e32 v[8:9], 0
	v_mov_b64_e32 v[10:11], 0
	v_mov_b64_e32 v[12:13], 0
	v_mov_b64_e32 v[14:15], 0
	v_mov_b64_e32 v[16:17], 0
	v_mov_b64_e32 v[18:19], 0
	v_mov_b64_e32 v[20:21], 0
	v_mov_b64_e32 v[22:23], 0
	v_mov_b64_e32 v[24:25], 0
	v_mov_b64_e32 v[26:27], 0
	v_mov_b64_e32 v[28:29], 0
	v_mov_b64_e32 v[30:31], 0
	v_mov_b64_e32 v[32:33], 0
	v_mov_b64_e32 v[34:35], 0
	v_mov_b64_e32 v[36:37], 0
	v_mov_b64_e32 v[38:39], 0
	v_mov_b64_e32 v[40:41], 0
	v_mov_b64_e32 v[42:43], 0
	v_mov_b64_e32 v[44:45], 0
	v_mov_b64_e32 v[46:47], 0
	v_mov_b64_e32 v[48:49], 0
	v_mov_b64_e32 v[50:51], 0
	v_mov_b64_e32 v[52:53], 0
	v_mov_b64_e32 v[54:55], 0
	v_mov_b64_e32 v[56:57], 0
	v_mov_b64_e32 v[58:59], 0
	v_mov_b64_e32 v[60:61], 0
	v_mov_b64_e32 v[62:63], 0
	v_mov_b64_e32 v[64:65], 0
	v_mov_b64_e32 v[66:67], 0
	v_mov_b64_e32 v[68:69], 0
	v_mov_b64_e32 v[70:71], 0
	v_mov_b64_e32 v[72:73], 0
	v_mov_b64_e32 v[74:75], 0
	v_mov_b64_e32 v[76:77], 0
	v_mov_b64_e32 v[78:79], 0
	v_mov_b64_e32 v[80:81], 0
	v_mov_b64_e32 v[82:83], 0
	v_mov_b64_e32 v[84:85], 0
	v_mov_b64_e32 v[86:87], 0
	v_mov_b64_e32 v[88:89], 0
	v_mov_b64_e32 v[90:91], 0
	v_mov_b64_e32 v[92:93], 0
	v_mov_b64_e32 v[94:95], 0
	v_mov_b64_e32 v[96:97], 0
	v_mov_b64_e32 v[98:99], 0
	v_mov_b64_e32 v[100:101], 0
	v_mov_b64_e32 v[102:103], 0
	v_mov_b64_e32 v[104:105], 0
	v_mov_b64_e32 v[106:107], 0
	v_mov_b64_e32 v[108:109], 0
	v_mov_b64_e32 v[110:111], 0
	v_mov_b64_e32 v[112:113], 0
	v_mov_b64_e32 v[114:115], 0
	v_mov_b64_e32 v[116:117], 0
	v_mov_b64_e32 v[118:119], 0
	v_mov_b64_e32 v[120:121], 0
	v_mov_b64_e32 v[122:123], 0
	v_mov_b64_e32 v[124:125], 0
	v_mov_b64_e32 v[126:127], 0

; #define PG8_STAGE(bufoff, gbase, voff) do { _Pragma("unroll") for (int _i = 0; _i < 2; ++_i) \
;         __builtin_amdgcn_global_load_lds((const unsigned*)((const char*)(gbase) + (voff)[_i]), (LAS unsigned*)(lds + (bufoff) + ldsw + _i * 8192), 16, 0, 0); } while (0)
; #define PG8_BAR __builtin_amdgcn_s_barrier()
; template <class Epi>
; __device__ __forceinline__ void gemm_phase(LAS unsigned char* lds, const Gemm g, const StaticOrder& S, const Epi& E, const int tid) {
;     ...
;     for (int i = 0; i < 2; ++i) { int R, C; stage_rc(tid * 16 + i * 8192, R, C); const int Rb = Epi::WIDE ? (64 * (R >> 5) + perm32(R & 31)) : ((R & ~31) + perm32(R & 31));
;         voffA[i] = g.a_tiled ? (unsigned)(((R >> 4) * (lda >> 5) + (C >> 5)) * 512 + (R & 15) * 32 + (C & 31)) * 2u : (unsigned)(R * lda + C) * 2u; voffB[i] = (unsigned)(Rb * K + C) * 2u; }
;     const size_t kstep = (size_t)(BK * 2), kstepA = g.a_tiled ? (size_t)2048 : kstep;
;     const size_t hstepA = (size_t)HALF * lda * 2, tstepA = 2 * hstepA;
;     const size_t hstepB = (size_t)(Epi::WIDE ? 32 : HALF) * K * 2, tstepB = (size_t)BM * K * 2;
;     const size_t pnoffA = (size_t)g.a_pn_off * 2;
;     const unsigned ldsw = (unsigned)wid * 1024u;
;     const int aoff = lds_byte(wr * 64 + fr, fq * 8), boff = lds_byte(wc * 32 + fr, fq * 8);
;     ...
;     Unit cur, nxt; int ui = 0;
;     if (!S.next(0, cur)) return;
;     float rs[2][4];
;     if constexpr (Epi::NEXT_RS) rows_rstd(E.SS, cur.pm * BM + wr * 64 + fr, fq, rs);
;     f32x4 acc[2][2][4][2];
; #pragma unroll
;     for (int a = 0; a < 2; ++a)
; #pragma unroll
;         for (int b = 0; b < 2; ++b)
; #pragma unroll
;             for (int m = 0; m < 4; ++m)
; #pragma unroll
;                 for (int n = 0; n < 2; ++n) acc[a][b][m][n] = (f32x4){0.f, 0.f, 0.f, 0.f};
;     bf16x8 At[4][2], B0[2][2], B1[2][2];
;     const char* cA = (const char*)g.A + (size_t)cur.pm * tstepA + (size_t)cur.pn * pnoffA; const char* cB = (const char*)g.Bt + (size_t)cur.pn * tstepB;
;     PG8_STAGE(PG8_SB(0, 0), cB, voffB); PG8_STAGE(PG8_SB(0, 1), cB + hstepB, voffB); PG8_STAGE(PG8_SA(0, 0), cA, voffA); PG8_STAGE(PG8_SA(0, 1), cA + hstepA, voffA);
;     if (wr == 1) PG8_BAR;
;     PG8_WAIT_V(2); PG8_BAR;
;     PG8_STAGE(PG8_SB(1, 0), cB + kstep, voffB); PG8_STAGE(PG8_SA(1, 0), cA + kstepA, voffA); PG8_STAGE(PG8_SB(1, 1), cB + hstepB + kstep, voffB);
;     PG8_WAIT_V(6); PG8_BAR;
.LBB0_447:
	s_and_b32 s44, s8, 3
	s_add_i32 m0, s23, 0x18000
	v_lshl_add_u64 v[6:7], v[6:7], 0, s[36:37]
	s_lshl_b32 s10, s5, 13
	s_lshl_b32 s11, s44, 12
	s_waitcnt vmcnt(2)
	s_barrier
	global_load_lds_dwordx4 v[6:7], off
	v_lshl_add_u64 v[4:5], v[4:5], 0, s[36:37]
	s_add_i32 m0, s23, 0x1a000
	s_add_i32 s45, s23, 0x8000
	s_add_i32 s46, s23, 0xa000
	global_load_lds_dwordx4 v[4:5], off
	v_lshl_add_u64 v[0:1], v[0:1], 0, s[76:77]
	s_mov_b32 m0, s45
	s_add_u32 s8, s28, 0x40080
	global_load_lds_dwordx4 v[0:1], off
	v_lshl_add_u64 v[0:1], v[2:3], 0, s[76:77]
	s_mov_b32 m0, s46
	s_addc_u32 s9, s29, 0
	global_load_lds_dwordx4 v[0:1], off
	s_add_i32 m0, s23, 0x1c000
	v_lshl_add_u64 v[0:1], s[8:9], 0, v[176:177]
	global_load_lds_dwordx4 v[0:1], off
	v_lshl_add_u64 v[0:1], s[8:9], 0, v[128:129]
	s_add_i32 m0, s23, 0x1e000
	v_lshlrev_b32_e32 v3, 2, v192
	global_load_lds_dwordx4 v[0:1], off
	v_and_b32_e32 v1, 15, v192
	v_and_b32_e32 v0, 48, v192
	v_lshlrev_b32_e32 v2, 6, v1
	s_cmpk_lt_u32 s4, 0x100
	v_lshl_or_b32 v142, s5, 6, v1
	v_or_b32_e32 v1, v2, v0
	v_and_b32_e32 v3, 32, v3
	s_cselect_b64 s[8:9], -1, 0
	s_lshl_b32 s47, s5, 2
	v_readlane_b32 s4, v254, 10
	v_bitop3_b32 v4, v1, s10, v3 bitop3:0xde
	v_bitop3_b32 v143, s11, v1, v3 bitop3:0xf6
	v_mov_b32_e32 v3, v177
	v_readlane_b32 s5, v254, 11
	v_mov_b32_e32 v1, v177
	v_lshl_add_u64 v[136:137], s[82:83], 0, v[0:1]
	v_lshl_add_u64 v[2:3], s[4:5], 0, v[2:3]
	v_lshl_add_u64 v[134:135], v[2:3], 0, v[0:1]
	v_lshlrev_b32_e32 v0, 9, v12
	v_and_b32_e32 v0, 0x7fffc000, v0
	v_lshl_add_u32 v0, v13, 9, v0
	v_or_b32_e32 v0, v0, v14
	v_add_lshl_u32 v0, v0, v15, 1
	s_mov_b64 s[4:5], 0x40800
	v_lshl_add_u64 v[138:139], v[0:1], 0, s[4:5]
	v_lshlrev_b32_e32 v0, 9, v8
	v_and_b32_e32 v0, 0x7fffc000, v0
	v_lshl_add_u32 v0, v9, 9, v0
	v_or_b32_e32 v0, v0, v10
	s_waitcnt vmcnt(6)
	v_add_lshl_u32 v0, v0, v11, 1
	v_lshl_add_u64 v[140:141], v[0:1], 0, s[4:5]
	v_readlane_b32 s4, v253, 23
	s_mov_b32 s48, 0
	v_add_u32_e32 v144, 0, v4
	v_lshlrev_b32_e32 v193, 4, v192
	v_add_u32_e32 v193, s22, v193
	v_readlane_b32 s49, v253, 11
	s_mov_b32 s50, s4
	s_barrier
	v_readlane_b32 s5, v253, 24
	s_branch .LBB0_450

; #define PG8_STAGE(bufoff, gbase, voff) do { _Pragma("unroll") for (int _i = 0; _i < 2; ++_i) \
;         __builtin_amdgcn_global_load_lds((const unsigned*)((const char*)(gbase) + (voff)[_i]), (LAS unsigned*)(lds + (bufoff) + ldsw + _i * 8192), 16, 0, 0); } while (0)
; #define PG8_LDA(dst, b, h) do { _Pragma("unroll") for (int m = 0; m < 4; ++m) _Pragma("unroll") for (int k = 0; k < 2; ++k) dst[m][k] = *(const LAS bf16x8*)(lds + PG8_SA(b, h) + aoff + m * 2048 + k * 1024); } while (0)
; #define PG8_LDB(dst, b, h) do { _Pragma("unroll") for (int n = 0; n < 2; ++n) _Pragma("unroll") for (int k = 0; k < 2; ++k) dst[n][k] = *(const LAS bf16x8*)(lds + PG8_SB(b, h) + boff + n * 2048 + k * 1024); } while (0)
; #define PG8_WAIT_V(n) asm volatile("s_waitcnt vmcnt(" #n ")" ::: "memory")
; #define PG8_WAIT_L(n) asm volatile("s_waitcnt lgkmcnt(" #n ")" ::: "memory")
; #define PG8_BAR __builtin_amdgcn_s_barrier()
; #define PG8_SCHED __builtin_amdgcn_sched_barrier(0)
; template <class Epi>
; __device__ __forceinline__ void gemm_phase(LAS unsigned char* lds, const Gemm g, const StaticOrder& S, const Epi& E, const int tid) {
;     ...
;         for (int t = 0; t < nt; t += 2) {
;             const bool last = (t == nt - 2);
;             const char* a1 = cA + (size_t)(t + 1) * kstepA;
;             const char* a2 = last ? nA : cA + (size_t)(t + 2) * kstepA; const char* b2 = last ? nB : cB + (size_t)(t + 2) * kstep;
;             const char* a3 = a2 + kstepA; const char* b3 = b2 + kstep;
;             PG8_LDB(B0, 0, 0); PG8_LDB(B1, 0, 1); PG8_SCHED; PG8_LDA(At, 0, 0); PG8_STAGE(PG8_SA(1, 1), a1 + hstepA, voffA);
;             PG8_WAIT_V(8); PG8_WAIT_L(0); PG8_BAR; PG8_MMA(0, 0, At, B0); PG8_MMA(0, 1, At, B1); PG8_BAR; PG8_SCHED;
;             PG8_LDA(At, 0, 1); PG8_STAGE(PG8_SB(0, 0), b2, voffB); PG8_STAGE(PG8_SB(0, 1), b2 + hstepB, voffB); PG8_STAGE(PG8_SA(0, 0), a2, voffA);
;             PG8_WAIT_V(8); PG8_WAIT_L(0); PG8_BAR; PG8_MMA(1, 0, At, B0); PG8_MMA(1, 1, At, B1); PG8_BAR; PG8_SCHED;
;     ...
; #pragma unroll
;         for (int a = 0; a < 2; ++a)
; #pragma unroll
;             for (int b = 0; b < 2; ++b)
; #pragma unroll
;                 for (int m = 0; m < 4; ++m)
; #pragma unroll
;                     for (int n = 0; n < 2; ++n) acc[a][b][m][n] = (f32x4){0.f, 0.f, 0.f, 0.f};
.LBB0_452:
	s_ashr_i32 s13, s12, 31
	s_lshl_b64 s[14:15], s[12:13], 19
	s_add_u32 s14, s24, s14
	s_addc_u32 s15, s25, s15
	s_and_b64 s[16:17], s[4:5], exec
	s_cselect_b32 s13, s15, s3
	s_cselect_b32 s51, s14, s2
	s_ashr_i32 s11, s10, 31
	s_lshl_b64 s[16:17], s[10:11], 19
	s_add_u32 s16, s20, s16
	s_addc_u32 s17, s21, s17
	s_and_b64 s[34:35], s[4:5], exec
	s_cselect_b32 s11, s17, s29
	s_cselect_b32 s52, s16, s28
	s_add_u32 s53, s28, 0x100
	v_mov_b32_e32 v0, 0
	s_addc_u32 s54, s29, 0
	s_mov_b32 s55, -2
	v_mov_b64_e32 v[0:1], 0
	v_mov_b64_e32 v[2:3], 0
	v_mov_b64_e32 v[4:5], 0
	v_mov_b64_e32 v[6:7], 0
	v_mov_b64_e32 v[8:9], 0
	v_mov_b64_e32 v[10:11], 0
	v_mov_b64_e32 v[12:13], 0
	v_mov_b64_e32 v[14:15], 0
	v_mov_b64_e32 v[16:17], 0
	v_mov_b64_e32 v[18:19], 0
	v_mov_b64_e32 v[20:21], 0
	v_mov_b64_e32 v[22:23], 0
	v_mov_b64_e32 v[24:25], 0
	v_mov_b64_e32 v[26:27], 0
	v_mov_b64_e32 v[28:29], 0
	v_mov_b64_e32 v[30:31], 0
	v_mov_b64_e32 v[32:33], 0
	v_mov_b64_e32 v[34:35], 0
	v_mov_b64_e32 v[36:37], 0
	v_mov_b64_e32 v[38:39], 0
	v_mov_b64_e32 v[40:41], 0
	v_mov_b64_e32 v[42:43], 0
	v_mov_b64_e32 v[44:45], 0
	v_mov_b64_e32 v[46:47], 0
	v_mov_b64_e32 v[48:49], 0
	v_mov_b64_e32 v[50:51], 0
	v_mov_b64_e32 v[52:53], 0
	v_mov_b64_e32 v[54:55], 0
	v_mov_b64_e32 v[56:57], 0
	v_mov_b64_e32 v[58:59], 0
	v_mov_b64_e32 v[60:61], 0
	v_mov_b64_e32 v[62:63], 0
	v_mov_b64_e32 v[64:65], 0
	v_mov_b64_e32 v[66:67], 0
	v_mov_b64_e32 v[68:69], 0
	v_mov_b64_e32 v[70:71], 0
	v_mov_b64_e32 v[72:73], 0
	v_mov_b64_e32 v[74:75], 0
	v_mov_b64_e32 v[76:77], 0
	v_mov_b64_e32 v[78:79], 0
	v_mov_b64_e32 v[80:81], 0
	v_mov_b64_e32 v[82:83], 0
	v_mov_b64_e32 v[84:85], 0
	v_mov_b64_e32 v[86:87], 0
	v_mov_b64_e32 v[88:89], 0
	v_mov_b64_e32 v[90:91], 0
	v_mov_b64_e32 v[92:93], 0
	v_mov_b64_e32 v[94:95], 0
	v_mov_b64_e32 v[96:97], 0
	v_mov_b64_e32 v[98:99], 0
	v_mov_b64_e32 v[100:101], 0
	v_mov_b64_e32 v[102:103], 0
	v_mov_b64_e32 v[104:105], 0
	v_mov_b64_e32 v[106:107], 0
	v_mov_b64_e32 v[108:109], 0
	v_mov_b64_e32 v[110:111], 0
	v_mov_b64_e32 v[112:113], 0
	v_mov_b64_e32 v[114:115], 0
	v_mov_b64_e32 v[116:117], 0
	v_mov_b64_e32 v[118:119], 0
	v_mov_b64_e32 v[120:121], 0
	v_mov_b64_e32 v[122:123], 0
	v_mov_b64_e32 v[124:125], 0
	v_mov_b64_e32 v[126:127], 0
.LBB0_453:
	s_add_u32 s28, s2, 0x1000
	s_addc_u32 s29, s3, 0
	s_add_i32 s56, 0, 0x10000
	s_cmp_eq_u32 s55, 12
	s_cselect_b32 s41, s13, s29
	s_cselect_b32 s40, s51, s28
	v_add_u32_e32 v145, s56, v143
	s_cselect_b32 s35, s11, s54
	s_cselect_b32 s34, s52, s53
	s_add_i32 s57, 0, 0x14000
	ds_read_b128 v[146:149], v145
	ds_read_b128 v[150:153], v145 offset:1024
	ds_read_b128 v[154:157], v145 offset:2048
	ds_read_b128 v[158:161], v145 offset:3072
	v_add_u32_e32 v145, s57, v143
	ds_read_b128 v[162:165], v145
	ds_read_b128 v[166:169], v145 offset:1024
	ds_read_b128 v[170:173], v145 offset:2048
	ds_read_b128 v[194:197], v145 offset:3072
	v_lshl_add_u64 v[174:175], s[2:3], 0, v[138:139]
	s_add_i32 m0, s23, 0xc000
	ds_read_b128 v[202:205], v144
	ds_read_b128 v[206:209], v144 offset:1024
	ds_read_b128 v[210:213], v144 offset:2048
	ds_read_b128 v[214:217], v144 offset:3072
	ds_read_b128 v[226:229], v144 offset:4096
	ds_read_b128 v[230:233], v144 offset:5120
	ds_read_b128 v[234:237], v144 offset:6144
	ds_read_b128 v[238:241], v144 offset:7168
	global_load_lds_dwordx4 v[174:175], off
	v_lshl_add_u64 v[174:175], s[2:3], 0, v[140:141]
	s_add_i32 m0, s23, 0xe000
	s_nop 0
	global_load_lds_dwordx4 v[174:175], off
	s_waitcnt vmcnt(8)
	s_waitcnt lgkmcnt(0)
	s_barrier
	s_setprio 1
	s_waitcnt lgkmcnt(0)
	v_mfma_f32_16x16x32_bf16 v[124:127], v[146:149], v[202:205], v[124:127]
	v_mfma_f32_16x16x32_bf16 v[116:119], v[154:157], v[202:205], v[116:119]
	v_mfma_f32_16x16x32_bf16 v[108:111], v[146:149], v[210:213], v[108:111]
	v_mfma_f32_16x16x32_bf16 v[100:103], v[154:157], v[210:213], v[100:103]
	v_mfma_f32_16x16x32_bf16 v[92:95], v[146:149], v[226:229], v[92:95]
	v_mfma_f32_16x16x32_bf16 v[84:87], v[154:157], v[226:229], v[84:87]
	v_mfma_f32_16x16x32_bf16 v[76:79], v[146:149], v[234:237], v[76:79]
	v_mfma_f32_16x16x32_bf16 v[68:71], v[154:157], v[234:237], v[68:71]
	v_mfma_f32_16x16x32_bf16 v[124:127], v[150:153], v[206:209], v[124:127]
	v_mfma_f32_16x16x32_bf16 v[116:119], v[158:161], v[206:209], v[116:119]
	v_mfma_f32_16x16x32_bf16 v[108:111], v[150:153], v[214:217], v[108:111]
	v_mfma_f32_16x16x32_bf16 v[100:103], v[158:161], v[214:217], v[100:103]
	v_mfma_f32_16x16x32_bf16 v[92:95], v[150:153], v[230:233], v[92:95]
	v_mfma_f32_16x16x32_bf16 v[84:87], v[158:161], v[230:233], v[84:87]
	v_mfma_f32_16x16x32_bf16 v[76:79], v[150:153], v[238:241], v[76:79]
	v_mfma_f32_16x16x32_bf16 v[68:71], v[158:161], v[238:241], v[68:71]
	s_setprio 0
	s_setprio 1
	v_mfma_f32_16x16x32_bf16 v[120:123], v[162:165], v[202:205], v[120:123]
	v_mfma_f32_16x16x32_bf16 v[112:115], v[170:173], v[202:205], v[112:115]
	v_mfma_f32_16x16x32_bf16 v[104:107], v[162:165], v[210:213], v[104:107]
	v_mfma_f32_16x16x32_bf16 v[96:99], v[170:173], v[210:213], v[96:99]
	v_mfma_f32_16x16x32_bf16 v[88:91], v[162:165], v[226:229], v[88:91]
	v_mfma_f32_16x16x32_bf16 v[80:83], v[170:173], v[226:229], v[80:83]
	v_mfma_f32_16x16x32_bf16 v[72:75], v[162:165], v[234:237], v[72:75]
	v_mfma_f32_16x16x32_bf16 v[64:67], v[170:173], v[234:237], v[64:67]
	v_mfma_f32_16x16x32_bf16 v[120:123], v[166:169], v[206:209], v[120:123]
	v_mfma_f32_16x16x32_bf16 v[112:115], v[194:197], v[206:209], v[112:115]
	v_mfma_f32_16x16x32_bf16 v[104:107], v[166:169], v[214:217], v[104:107]
	v_mfma_f32_16x16x32_bf16 v[96:99], v[194:197], v[214:217], v[96:99]
	v_mfma_f32_16x16x32_bf16 v[88:91], v[166:169], v[230:233], v[88:91]
	v_mfma_f32_16x16x32_bf16 v[80:83], v[194:197], v[230:233], v[80:83]
	v_mfma_f32_16x16x32_bf16 v[72:75], v[166:169], v[238:241], v[72:75]
	v_mfma_f32_16x16x32_bf16 v[64:67], v[194:197], v[238:241], v[64:67]
	s_setprio 0
	s_barrier
	s_cmp_lg_u32 s55, -2
	s_cbranch_scc1 .Lswi_ss_skip
	s_lshl_b32 s100, s50, 14
	s_add_u32 s100, s82, s100
	s_addc_u32 s101, s83, 0
	s_lshl_b32 m0, s22, 1
	s_add_i32 m0, m0, 0x20800
	s_nop 0
	global_load_lds_dwordx4 v193, s[100:101]
	global_load_lds_dwordx4 v193, s[100:101] offset:1024
; #define PG8_STAGE(bufoff, gbase, voff) do { _Pragma("unroll") for (int _i = 0; _i < 2; ++_i) \
;         __builtin_amdgcn_global_load_lds((const unsigned*)((const char*)(gbase) + (voff)[_i]), (LAS unsigned*)(lds + (bufoff) + ldsw + _i * 8192), 16, 0, 0); } while (0)
; #define PG8_LDA(dst, b, h) do { _Pragma("unroll") for (int m = 0; m < 4; ++m) _Pragma("unroll") for (int k = 0; k < 2; ++k) dst[m][k] = *(const LAS bf16x8*)(lds + PG8_SA(b, h) + aoff + m * 2048 + k * 1024); } while (0)
; #define PG8_LDB(dst, b, h) do { _Pragma("unroll") for (int n = 0; n < 2; ++n) _Pragma("unroll") for (int k = 0; k < 2; ++k) dst[n][k] = *(const LAS bf16x8*)(lds + PG8_SB(b, h) + boff + n * 2048 + k * 1024); } while (0)
; #define PG8_MMA(ai, bj, At, Bt) do { __builtin_amdgcn_s_setprio(1); _Pragma("unroll") for (int m = 0; m < 4; ++m) _Pragma("unroll") for (int n = 0; n < 2; ++n) _Pragma("unroll") for (int k = 0; k < 2; ++k) \
;         acc[ai][bj][m][n] = __builtin_amdgcn_mfma_f32_16x16x32_bf16(Bt[n][k], At[m][k], acc[ai][bj][m][n], 0, 0, 0); __builtin_amdgcn_s_setprio(0); } while (0)
; #define PG8_WAIT_V(n) asm volatile("s_waitcnt vmcnt(" #n ")" ::: "memory")
; #define PG8_WAIT_L(n) asm volatile("s_waitcnt lgkmcnt(" #n ")" ::: "memory")
; #define PG8_BAR __builtin_amdgcn_s_barrier()
; #define PG8_SCHED __builtin_amdgcn_sched_barrier(0)
; template <class Epi>
; __device__ __forceinline__ void gemm_phase(LAS unsigned char* lds, const Gemm g, const StaticOrder& S, const Epi& E, const int tid) {
;     ...
;             PG8_LDA(At, 0, 1); PG8_STAGE(PG8_SB(0, 0), b2, voffB); PG8_STAGE(PG8_SB(0, 1), b2 + hstepB, voffB); PG8_STAGE(PG8_SA(0, 0), a2, voffA);
;             PG8_WAIT_V(8); PG8_WAIT_L(0); PG8_BAR; PG8_MMA(1, 0, At, B0); PG8_MMA(1, 1, At, B1); PG8_BAR; PG8_SCHED;
;             PG8_LDB(B0, 1, 0); PG8_LDB(B1, 1, 1); PG8_SCHED; PG8_LDA(At, 1, 0); PG8_STAGE(PG8_SA(0, 1), a2 + hstepA, voffA);
;             PG8_WAIT_V(8); PG8_WAIT_L(0); PG8_BAR; PG8_MMA(0, 0, At, B0); PG8_MMA(0, 1, At, B1); PG8_BAR; PG8_SCHED;
;             PG8_LDA(At, 1, 1); PG8_STAGE(PG8_SB(1, 0), b3, voffB); PG8_STAGE(PG8_SB(1, 1), b3 + hstepB, voffB); PG8_STAGE(PG8_SA(1, 0), a3, voffA);
.Lswi_ss_skip:
	s_add_i32 s2, s56, s22
	v_lshl_add_u64 v[174:175], s[34:35], 0, v[176:177]
	s_mov_b32 m0, s2
	ds_read_b128 v[202:205], v144 offset:16384
	ds_read_b128 v[206:209], v144 offset:17408
	ds_read_b128 v[210:213], v144 offset:18432
	ds_read_b128 v[214:217], v144 offset:19456
	ds_read_b128 v[226:229], v144 offset:20480
	ds_read_b128 v[230:233], v144 offset:21504
	ds_read_b128 v[234:237], v144 offset:22528
	ds_read_b128 v[238:241], v144 offset:23552
	global_load_lds_dwordx4 v[174:175], off
	s_add_i32 m0, s2, 0x2000
	s_add_u32 s2, s34, 0x40000
	v_lshl_add_u64 v[178:179], s[34:35], 0, v[128:129]
	s_addc_u32 s3, s35, 0
	s_add_i32 s56, s57, s22
	global_load_lds_dwordx4 v[178:179], off
	v_lshl_add_u64 v[180:181], s[2:3], 0, v[176:177]
	s_mov_b32 m0, s56
	v_lshl_add_u64 v[198:199], s[40:41], 0, v[130:131]
	global_load_lds_dwordx4 v[180:181], off
	v_lshl_add_u64 v[180:181], s[2:3], 0, v[128:129]
	s_add_i32 m0, s56, 0x2000
	s_nop 0
	global_load_lds_dwordx4 v[180:181], off
	v_lshl_add_u64 v[180:181], s[40:41], 0, v[132:133]
	s_mov_b32 m0, s23
	s_nop 0
	global_load_lds_dwordx4 v[180:181], off
	s_mov_b32 m0, s30
	s_nop 0
	global_load_lds_dwordx4 v[198:199], off
	s_waitcnt vmcnt(8)
	s_waitcnt lgkmcnt(0)
	s_barrier
	s_setprio 1
	s_waitcnt lgkmcnt(0)
	v_mfma_f32_16x16x32_bf16 v[60:63], v[146:149], v[202:205], v[60:63]
	v_mfma_f32_16x16x32_bf16 v[52:55], v[154:157], v[202:205], v[52:55]
	v_mfma_f32_16x16x32_bf16 v[44:47], v[146:149], v[210:213], v[44:47]
	v_mfma_f32_16x16x32_bf16 v[36:39], v[154:157], v[210:213], v[36:39]
	v_mfma_f32_16x16x32_bf16 v[28:31], v[146:149], v[226:229], v[28:31]
	v_mfma_f32_16x16x32_bf16 v[20:23], v[154:157], v[226:229], v[20:23]
	v_mfma_f32_16x16x32_bf16 v[12:15], v[146:149], v[234:237], v[12:15]
	v_mfma_f32_16x16x32_bf16 v[4:7], v[154:157], v[234:237], v[4:7]
	v_mfma_f32_16x16x32_bf16 v[60:63], v[150:153], v[206:209], v[60:63]
	v_mfma_f32_16x16x32_bf16 v[52:55], v[158:161], v[206:209], v[52:55]
	v_mfma_f32_16x16x32_bf16 v[44:47], v[150:153], v[214:217], v[44:47]
	v_mfma_f32_16x16x32_bf16 v[36:39], v[158:161], v[214:217], v[36:39]
	v_mfma_f32_16x16x32_bf16 v[28:31], v[150:153], v[230:233], v[28:31]
	v_mfma_f32_16x16x32_bf16 v[20:23], v[158:161], v[230:233], v[20:23]
	v_mfma_f32_16x16x32_bf16 v[12:15], v[150:153], v[238:241], v[12:15]
	v_mfma_f32_16x16x32_bf16 v[4:7], v[158:161], v[238:241], v[4:7]
	s_setprio 0
	s_setprio 1
	v_mfma_f32_16x16x32_bf16 v[56:59], v[162:165], v[202:205], v[56:59]
	v_mfma_f32_16x16x32_bf16 v[48:51], v[170:173], v[202:205], v[48:51]
	v_mfma_f32_16x16x32_bf16 v[40:43], v[162:165], v[210:213], v[40:43]
	v_mfma_f32_16x16x32_bf16 v[32:35], v[170:173], v[210:213], v[32:35]
	v_mfma_f32_16x16x32_bf16 v[24:27], v[162:165], v[226:229], v[24:27]
	v_mfma_f32_16x16x32_bf16 v[16:19], v[170:173], v[226:229], v[16:19]
	v_mfma_f32_16x16x32_bf16 v[8:11], v[162:165], v[234:237], v[8:11]
	v_mfma_f32_16x16x32_bf16 v[0:3], v[170:173], v[234:237], v[0:3]
	v_mfma_f32_16x16x32_bf16 v[56:59], v[166:169], v[206:209], v[56:59]
	v_mfma_f32_16x16x32_bf16 v[48:51], v[194:197], v[206:209], v[48:51]
	v_mfma_f32_16x16x32_bf16 v[40:43], v[166:169], v[214:217], v[40:43]
	v_mfma_f32_16x16x32_bf16 v[32:35], v[194:197], v[214:217], v[32:35]
	v_mfma_f32_16x16x32_bf16 v[24:27], v[166:169], v[230:233], v[24:27]
	v_mfma_f32_16x16x32_bf16 v[16:19], v[194:197], v[230:233], v[16:19]
	v_mfma_f32_16x16x32_bf16 v[8:11], v[166:169], v[238:241], v[8:11]
	v_mfma_f32_16x16x32_bf16 v[0:3], v[194:197], v[238:241], v[0:3]
	s_setprio 0
	s_barrier
	s_add_i32 s56, 0, 0x18000
	v_add_u32_e32 v145, s56, v143
	s_add_i32 s57, 0, 0x1c000
	ds_read_b128 v[146:149], v145
	ds_read_b128 v[150:153], v145 offset:1024
	ds_read_b128 v[154:157], v145 offset:2048
	ds_read_b128 v[158:161], v145 offset:3072
	v_add_u32_e32 v145, s57, v143
	ds_read_b128 v[162:165], v145
	ds_read_b128 v[166:169], v145 offset:1024
	ds_read_b128 v[170:173], v145 offset:2048
	ds_read_b128 v[194:197], v145 offset:3072
	s_add_u32 s2, s40, 0x40000
	s_addc_u32 s3, s41, 0
	s_mov_b32 m0, s42
	v_lshl_add_u64 v[218:219], s[2:3], 0, v[132:133]
	ds_read_b128 v[202:205], v144 offset:32768
	ds_read_b128 v[206:209], v144 offset:33792
	ds_read_b128 v[210:213], v144 offset:34816
	ds_read_b128 v[214:217], v144 offset:35840
	ds_read_b128 v[226:229], v144 offset:36864
	ds_read_b128 v[230:233], v144 offset:37888
	ds_read_b128 v[234:237], v144 offset:38912
	ds_read_b128 v[238:241], v144 offset:39936
	global_load_lds_dwordx4 v[218:219], off
	v_lshl_add_u64 v[218:219], s[2:3], 0, v[130:131]
	s_mov_b32 m0, s43
	s_nop 0
	global_load_lds_dwordx4 v[218:219], off
	s_waitcnt vmcnt(8)
	s_waitcnt lgkmcnt(0)
	s_barrier
; #define PG8_STAGE(bufoff, gbase, voff) do { _Pragma("unroll") for (int _i = 0; _i < 2; ++_i) \
;         __builtin_amdgcn_global_load_lds((const unsigned*)((const char*)(gbase) + (voff)[_i]), (LAS unsigned*)(lds + (bufoff) + ldsw + _i * 8192), 16, 0, 0); } while (0)
; #define PG8_LDA(dst, b, h) do { _Pragma("unroll") for (int m = 0; m < 4; ++m) _Pragma("unroll") for (int k = 0; k < 2; ++k) dst[m][k] = *(const LAS bf16x8*)(lds + PG8_SA(b, h) + aoff + m * 2048 + k * 1024); } while (0)
; #define PG8_LDB(dst, b, h) do { _Pragma("unroll") for (int n = 0; n < 2; ++n) _Pragma("unroll") for (int k = 0; k < 2; ++k) dst[n][k] = *(const LAS bf16x8*)(lds + PG8_SB(b, h) + boff + n * 2048 + k * 1024); } while (0)
; #define PG8_MMA(ai, bj, At, Bt) do { __builtin_amdgcn_s_setprio(1); _Pragma("unroll") for (int m = 0; m < 4; ++m) _Pragma("unroll") for (int n = 0; n < 2; ++n) _Pragma("unroll") for (int k = 0; k < 2; ++k) \
;         acc[ai][bj][m][n] = __builtin_amdgcn_mfma_f32_16x16x32_bf16(Bt[n][k], At[m][k], acc[ai][bj][m][n], 0, 0, 0); __builtin_amdgcn_s_setprio(0); } while (0)
; #define PG8_WAIT_V(n) asm volatile("s_waitcnt vmcnt(" #n ")" ::: "memory")
; #define PG8_WAIT_L(n) asm volatile("s_waitcnt lgkmcnt(" #n ")" ::: "memory")
; #define PG8_BAR __builtin_amdgcn_s_barrier()
; #define PG8_SCHED __builtin_amdgcn_sched_barrier(0)
; template <class Epi>
; __device__ __forceinline__ void gemm_phase(LAS unsigned char* lds, const Gemm g, const StaticOrder& S, const Epi& E, const int tid) {
;     ...
;             PG8_LDB(B0, 1, 0); PG8_LDB(B1, 1, 1); PG8_SCHED; PG8_LDA(At, 1, 0); PG8_STAGE(PG8_SA(0, 1), a2 + hstepA, voffA);
;             PG8_WAIT_V(8); PG8_WAIT_L(0); PG8_BAR; PG8_MMA(0, 0, At, B0); PG8_MMA(0, 1, At, B1); PG8_BAR; PG8_SCHED;
;             PG8_LDA(At, 1, 1); PG8_STAGE(PG8_SB(1, 0), b3, voffB); PG8_STAGE(PG8_SB(1, 1), b3 + hstepB, voffB); PG8_STAGE(PG8_SA(1, 0), a3, voffA);
;             PG8_WAIT_V(8); PG8_WAIT_L(0); PG8_BAR; PG8_MMA(1, 0, At, B0); PG8_MMA(1, 1, At, B1); PG8_BAR; PG8_SCHED;
;         }
;         if (wr == 0) PG8_BAR;
	s_setprio 1
	s_waitcnt lgkmcnt(0)
	v_mfma_f32_16x16x32_bf16 v[124:127], v[146:149], v[202:205], v[124:127]
	v_mfma_f32_16x16x32_bf16 v[116:119], v[154:157], v[202:205], v[116:119]
	v_mfma_f32_16x16x32_bf16 v[108:111], v[146:149], v[210:213], v[108:111]
	v_mfma_f32_16x16x32_bf16 v[100:103], v[154:157], v[210:213], v[100:103]
	v_mfma_f32_16x16x32_bf16 v[92:95], v[146:149], v[226:229], v[92:95]
	v_mfma_f32_16x16x32_bf16 v[84:87], v[154:157], v[226:229], v[84:87]
	v_mfma_f32_16x16x32_bf16 v[76:79], v[146:149], v[234:237], v[76:79]
	v_mfma_f32_16x16x32_bf16 v[68:71], v[154:157], v[234:237], v[68:71]
	v_mfma_f32_16x16x32_bf16 v[124:127], v[150:153], v[206:209], v[124:127]
	v_mfma_f32_16x16x32_bf16 v[116:119], v[158:161], v[206:209], v[116:119]
	v_mfma_f32_16x16x32_bf16 v[108:111], v[150:153], v[214:217], v[108:111]
	v_mfma_f32_16x16x32_bf16 v[100:103], v[158:161], v[214:217], v[100:103]
	v_mfma_f32_16x16x32_bf16 v[92:95], v[150:153], v[230:233], v[92:95]
	v_mfma_f32_16x16x32_bf16 v[84:87], v[158:161], v[230:233], v[84:87]
	v_mfma_f32_16x16x32_bf16 v[76:79], v[150:153], v[238:241], v[76:79]
	v_mfma_f32_16x16x32_bf16 v[68:71], v[158:161], v[238:241], v[68:71]
	s_setprio 0
	s_setprio 1
	v_mfma_f32_16x16x32_bf16 v[120:123], v[162:165], v[202:205], v[120:123]
	v_mfma_f32_16x16x32_bf16 v[112:115], v[170:173], v[202:205], v[112:115]
	v_mfma_f32_16x16x32_bf16 v[104:107], v[162:165], v[210:213], v[104:107]
	v_mfma_f32_16x16x32_bf16 v[96:99], v[170:173], v[210:213], v[96:99]
	v_mfma_f32_16x16x32_bf16 v[88:91], v[162:165], v[226:229], v[88:91]
	v_mfma_f32_16x16x32_bf16 v[80:83], v[170:173], v[226:229], v[80:83]
	v_mfma_f32_16x16x32_bf16 v[72:75], v[162:165], v[234:237], v[72:75]
	v_mfma_f32_16x16x32_bf16 v[64:67], v[170:173], v[234:237], v[64:67]
	v_mfma_f32_16x16x32_bf16 v[120:123], v[166:169], v[206:209], v[120:123]
	v_mfma_f32_16x16x32_bf16 v[112:115], v[194:197], v[206:209], v[112:115]
	v_mfma_f32_16x16x32_bf16 v[104:107], v[166:169], v[214:217], v[104:107]
	v_mfma_f32_16x16x32_bf16 v[96:99], v[194:197], v[214:217], v[96:99]
	v_mfma_f32_16x16x32_bf16 v[88:91], v[166:169], v[230:233], v[88:91]
	v_mfma_f32_16x16x32_bf16 v[80:83], v[194:197], v[230:233], v[80:83]
	v_mfma_f32_16x16x32_bf16 v[72:75], v[166:169], v[238:241], v[72:75]
	v_mfma_f32_16x16x32_bf16 v[64:67], v[194:197], v[238:241], v[64:67]
	s_setprio 0
	s_barrier
	s_add_i32 s2, s56, s22
	v_lshl_add_u64 v[174:175], v[174:175], 0, s[36:37]
	s_mov_b32 m0, s2
	ds_read_b128 v[202:205], v144 offset:49152
	ds_read_b128 v[206:209], v144 offset:50176
	ds_read_b128 v[210:213], v144 offset:51200
	ds_read_b128 v[214:217], v144 offset:52224
	ds_read_b128 v[226:229], v144 offset:53248
	ds_read_b128 v[230:233], v144 offset:54272
	ds_read_b128 v[234:237], v144 offset:55296
	ds_read_b128 v[238:241], v144 offset:56320
	global_load_lds_dwordx4 v[174:175], off
	s_add_i32 m0, s2, 0x2000
	s_add_u32 s2, s34, 0x40080
	v_lshl_add_u64 v[174:175], v[178:179], 0, s[36:37]
	s_addc_u32 s3, s35, 0
	s_add_i32 s34, s57, s22
	global_load_lds_dwordx4 v[174:175], off
	v_lshl_add_u64 v[174:175], s[2:3], 0, v[176:177]
	s_mov_b32 m0, s34
	s_nop 0
	global_load_lds_dwordx4 v[174:175], off
	v_lshl_add_u64 v[174:175], s[2:3], 0, v[128:129]
	s_add_i32 m0, s34, 0x2000
	s_nop 0
	global_load_lds_dwordx4 v[174:175], off
	v_lshl_add_u64 v[174:175], v[180:181], 0, s[76:77]
	s_mov_b32 m0, s45
	s_nop 0
	global_load_lds_dwordx4 v[174:175], off
	v_lshl_add_u64 v[174:175], v[198:199], 0, s[76:77]
	s_mov_b32 m0, s46
	s_nop 0
	global_load_lds_dwordx4 v[174:175], off
	s_waitcnt vmcnt(8)
	s_waitcnt lgkmcnt(0)
	s_barrier
	s_setprio 1
	s_waitcnt lgkmcnt(0)
	v_mfma_f32_16x16x32_bf16 v[60:63], v[146:149], v[202:205], v[60:63]
	v_mfma_f32_16x16x32_bf16 v[52:55], v[154:157], v[202:205], v[52:55]
	v_mfma_f32_16x16x32_bf16 v[44:47], v[146:149], v[210:213], v[44:47]
	v_mfma_f32_16x16x32_bf16 v[36:39], v[154:157], v[210:213], v[36:39]
	v_mfma_f32_16x16x32_bf16 v[28:31], v[146:149], v[226:229], v[28:31]
	v_mfma_f32_16x16x32_bf16 v[20:23], v[154:157], v[226:229], v[20:23]
	v_mfma_f32_16x16x32_bf16 v[12:15], v[146:149], v[234:237], v[12:15]
	v_mfma_f32_16x16x32_bf16 v[4:7], v[154:157], v[234:237], v[4:7]
	v_mfma_f32_16x16x32_bf16 v[60:63], v[150:153], v[206:209], v[60:63]
	v_mfma_f32_16x16x32_bf16 v[52:55], v[158:161], v[206:209], v[52:55]
	v_mfma_f32_16x16x32_bf16 v[44:47], v[150:153], v[214:217], v[44:47]
	v_mfma_f32_16x16x32_bf16 v[36:39], v[158:161], v[214:217], v[36:39]
	v_mfma_f32_16x16x32_bf16 v[28:31], v[150:153], v[230:233], v[28:31]
	v_mfma_f32_16x16x32_bf16 v[20:23], v[158:161], v[230:233], v[20:23]
	v_mfma_f32_16x16x32_bf16 v[12:15], v[150:153], v[238:241], v[12:15]
	v_mfma_f32_16x16x32_bf16 v[4:7], v[158:161], v[238:241], v[4:7]
	s_setprio 0
	s_setprio 1
	v_mfma_f32_16x16x32_bf16 v[56:59], v[162:165], v[202:205], v[56:59]
	v_mfma_f32_16x16x32_bf16 v[48:51], v[170:173], v[202:205], v[48:51]
	v_mfma_f32_16x16x32_bf16 v[40:43], v[162:165], v[210:213], v[40:43]
	v_mfma_f32_16x16x32_bf16 v[32:35], v[170:173], v[210:213], v[32:35]
	v_mfma_f32_16x16x32_bf16 v[24:27], v[162:165], v[226:229], v[24:27]
	v_mfma_f32_16x16x32_bf16 v[16:19], v[170:173], v[226:229], v[16:19]
	v_mfma_f32_16x16x32_bf16 v[8:11], v[162:165], v[234:237], v[8:11]
	v_mfma_f32_16x16x32_bf16 v[0:3], v[170:173], v[234:237], v[0:3]
	v_mfma_f32_16x16x32_bf16 v[56:59], v[166:169], v[206:209], v[56:59]
	v_mfma_f32_16x16x32_bf16 v[48:51], v[194:197], v[206:209], v[48:51]
	v_mfma_f32_16x16x32_bf16 v[40:43], v[166:169], v[214:217], v[40:43]
	v_mfma_f32_16x16x32_bf16 v[32:35], v[194:197], v[214:217], v[32:35]
	v_mfma_f32_16x16x32_bf16 v[24:27], v[166:169], v[230:233], v[24:27]
	v_mfma_f32_16x16x32_bf16 v[16:19], v[194:197], v[230:233], v[16:19]
	v_mfma_f32_16x16x32_bf16 v[8:11], v[166:169], v[238:241], v[8:11]
	v_mfma_f32_16x16x32_bf16 v[0:3], v[194:197], v[238:241], v[0:3]
	s_setprio 0
	s_barrier
	s_add_i32 s55, s55, 2
	s_add_u32 s53, s53, 0x100
	s_addc_u32 s54, s54, 0
	s_cmp_gt_u32 s55, 13
	s_mov_b64 s[2:3], s[28:29]
	s_cbranch_scc0 .LBB0_453
	s_and_b64 vcc, exec, s[8:9]
	s_cbranch_vccz .LBB0_456
	s_barrier
; __device__ __forceinline__ unsigned cvtpk(float lo, float hi) { f32x2_t v = {lo, hi}; bf16x2_t b = __builtin_convertvector(v, bf16x2_t); return __builtin_bit_cast(unsigned, b); }
; __device__ __forceinline__ f32x4 gload16(const void* p) { f32x4 v; asm volatile("global_load_dwordx4 %0, %1, off" : "=v"(v) : "v"(p) : "memory"); return v; }
; #define WAIT8(a) asm volatile("s_waitcnt vmcnt(0)" : "+v"(a[0]), "+v"(a[1]), "+v"(a[2]), "+v"(a[3]), "+v"(a[4]), "+v"(a[5]), "+v"(a[6]), "+v"(a[7]) :: "memory")
; __device__ __forceinline__ void rows_rstd(const float* SS, int row0, int fq, float (&rs)[2][4]) {
;     f32x4 p[8];
; #pragma unroll
;     for (int i = 0; i < 8; ++i) p[i] = gload16(SS + (size_t)(row0 + (i >> 2) * HALF + (i & 3) * 16) * 16 + fq * 4);
;     WAIT8(p);
; #pragma unroll
;     for (int i = 0; i < 8; ++i) {
;         float s = (p[i].x + p[i].y) + (p[i].z + p[i].w);
;         s += __shfl_xor(s, 16); s += __shfl_xor(s, 32);
;         rs[i >> 2][i & 3] = __builtin_amdgcn_rsqf(s * (1.f / D) + EPS);
;     }
; }
;     __device__ __forceinline__ void operator()(const AccT& acc, const Unit& u, int wr, int wc, int fr, int fq, LAS unsigned char* stg) const {
;         const int row0 = u.pm * BM + wr * 64 + fr;
;         float rs[2][4];
;         rows_rstd(SS, row0, fq, rs);
; #pragma unroll
;         for (int ai = 0; ai < 2; ++ai)
; #pragma unroll
;             for (int m = 0; m < 4; ++m) {
;                 bf16_t* rowp = O + ((size_t)(u.pm * 16 + wr * 4 + ai * 8 + m) * (ldo >> 5) + (u.pn * 4 + wc)) * 512 + fr * 32 + 8 * fq;
;                 const float k1 = rs[ai][m] * -1.4426950408889634f, k2 = rs[ai][m] * rs[ai][m];
;                 float r[8];
; #pragma unroll
;                 for (int n = 0; n < 2; ++n)
; #pragma unroll
;                     for (int i = 0; i < 4; ++i) {
;                         const float g = acc[ai][0][m][n][i], up = acc[ai][1][m][n][i];
;                         const float e = __builtin_amdgcn_exp2f(g * k1);
;                         r[n * 4 + i] = (g * up) * (k2 * __builtin_amdgcn_rcpf(1.0f + e));
;                     }
;                 u32x4 w; w.x = cvtpk(r[0], r[1]); w.y = cvtpk(r[2], r[3]); w.z = cvtpk(r[4], r[5]); w.w = cvtpk(r[6], r[7]);
;                 __builtin_nontemporal_store(w, (u32x4*)rowp);
.LBB0_456:
	v_and_b32_e32 v145, 48, v223
	v_lshl_add_u32 v145, v142, 6, v145
	v_add_u32_e32 v145, 0x20800, v145
	ds_read_b128 v[146:149], v145
	ds_read_b128 v[150:153], v145 offset:1024
	ds_read_b128 v[154:157], v145 offset:2048
	ds_read_b128 v[158:161], v145 offset:3072
	ds_read_b128 v[162:165], v145 offset:8192
	ds_read_b128 v[166:169], v145 offset:9216
	ds_read_b128 v[170:173], v145 offset:10240
	ds_read_b128 v[194:197], v145 offset:11264
	v_and_b32_e32 v174, 64, v223
	s_waitcnt lgkmcnt(0)
	v_xor_b32_e32 v145, 16, v223
	v_add_u32_e32 v178, 64, v174
	v_cmp_lt_i32_e32 vcc, v145, v178
	v_mov_b32_e32 v174, v147
	v_mov_b32_e32 v175, v148
	v_mov_b32_e32 v147, v149
	v_cndmask_b32_e32 v145, v223, v145, vcc
	v_pk_add_f32 v[146:147], v[174:175], v[146:147]
	v_lshlrev_b32_e32 v145, 2, v145
	v_add_f32_e32 v146, v146, v147
	ds_bpermute_b32 v147, v145, v146
	v_xor_b32_e32 v148, 32, v223
	v_cmp_lt_i32_e32 vcc, v148, v178
	v_pk_mul_f32 v[122:123], v[126:127], v[122:123]
	v_pk_mul_f32 v[120:121], v[124:125], v[120:121]
	v_cndmask_b32_e32 v148, v223, v148, vcc
	v_lshlrev_b32_e32 v148, 2, v148
	s_waitcnt lgkmcnt(0)
	v_add_f32_e32 v146, v146, v147
	ds_bpermute_b32 v147, v148, v146
	v_pk_mul_f32 v[114:115], v[118:119], v[114:115]
	s_lshl_b32 s11, s50, 4
	s_lshl_b32 s2, s49, 2
	s_add_i32 s11, s11, s47
	s_waitcnt lgkmcnt(0)
	v_add_f32_e32 v149, v146, v147
	v_mov_b32_e32 v146, v151
	v_mov_b32_e32 v147, v152
	v_mov_b32_e32 v151, v153
	v_pk_add_f32 v[146:147], v[146:147], v[150:151]
	v_fmamk_f32 v149, v149, 0x3a800000, v220
	v_add_f32_e32 v150, v146, v147
	v_mov_b32_e32 v146, v155
	v_mov_b32_e32 v147, v156
	v_mov_b32_e32 v155, v157
	v_pk_add_f32 v[146:147], v[146:147], v[154:155]
	ds_bpermute_b32 v151, v145, v150
	v_add_f32_e32 v146, v146, v147
	ds_bpermute_b32 v147, v145, v146
	v_rsq_f32_e32 v149, v149
	s_or_b32 s2, s2, s44
	s_waitcnt lgkmcnt(0)
	v_add_f32_e32 v150, v150, v151
	ds_bpermute_b32 v151, v148, v150
	v_add_f32_e32 v152, v146, v147
	v_mov_b32_e32 v146, v159
	v_mov_b32_e32 v147, v160
	v_mov_b32_e32 v159, v161
	v_pk_add_f32 v[146:147], v[146:147], v[158:159]
	ds_bpermute_b32 v153, v148, v152
	v_add_f32_e32 v146, v146, v147
	ds_bpermute_b32 v147, v145, v146
	s_waitcnt lgkmcnt(0)
	v_add_f32_e32 v150, v150, v151
	v_fmamk_f32 v150, v150, 0x3a800000, v220
	v_rsq_f32_e32 v154, v150
	v_add_f32_e32 v150, v152, v153
	v_add_f32_e32 v151, v146, v147
	v_mov_b32_e32 v146, v163
	v_mov_b32_e32 v147, v164
	v_mov_b32_e32 v163, v165
	v_pk_add_f32 v[146:147], v[146:147], v[162:163]
	ds_bpermute_b32 v152, v148, v151
	v_add_f32_e32 v146, v146, v147
	ds_bpermute_b32 v147, v145, v146
	v_fmamk_f32 v150, v150, 0x3a800000, v220
	v_rsq_f32_e32 v153, v150
	s_waitcnt lgkmcnt(0)
	v_add_f32_e32 v150, v151, v152
	v_fmamk_f32 v150, v150, 0x3a800000, v220
	v_add_f32_e32 v151, v146, v147
	v_mov_b32_e32 v146, v167
	v_mov_b32_e32 v147, v168
	v_mov_b32_e32 v167, v169
	ds_bpermute_b32 v152, v148, v151
	v_pk_add_f32 v[146:147], v[146:147], v[166:167]
	v_rsq_f32_e32 v155, v150
	v_add_f32_e32 v146, v146, v147
	ds_bpermute_b32 v147, v145, v146
	s_waitcnt lgkmcnt(0)
	v_add_f32_e32 v150, v151, v152
	v_fmamk_f32 v150, v150, 0x3a800000, v220
	v_rsq_f32_e32 v152, v150
	s_ashr_i32 s3, s2, 31
	v_add_f32_e32 v150, v146, v147
	v_mov_b32_e32 v146, v171
	v_mov_b32_e32 v147, v172
	v_mov_b32_e32 v171, v173
	v_pk_add_f32 v[146:147], v[146:147], v[170:171]
	ds_bpermute_b32 v151, v148, v150
	v_add_f32_e32 v156, v146, v147
	v_mov_b32_e32 v146, v195
	v_mov_b32_e32 v147, v196
	v_mov_b32_e32 v195, v197
	v_pk_add_f32 v[146:147], v[146:147], v[194:195]
	ds_bpermute_b32 v157, v145, v156
	v_add_f32_e32 v146, v146, v147
	ds_bpermute_b32 v145, v145, v146
	s_waitcnt lgkmcnt(0)
	v_add_f32_e32 v147, v150, v151
	s_mul_i32 s13, s11, 0x58
	v_add_f32_e32 v150, v156, v157
	ds_bpermute_b32 v151, v148, v150
	v_add_f32_e32 v145, v146, v145
	ds_bpermute_b32 v148, v148, v145
	v_mul_f32_e32 v156, 0xbfb8aa3b, v149
	v_mul_f32_e32 v157, v127, v156
	s_waitcnt lgkmcnt(0)
	v_add_f32_e32 v146, v150, v151
	v_exp_f32_e32 v157, v157
	v_add_f32_e32 v145, v145, v148
	v_mul_f32_e32 v148, v124, v156
	v_exp_f32_e32 v150, v148
	v_mul_f32_e32 v148, v125, v156
	v_exp_f32_e32 v151, v148
	v_mul_f32_e32 v148, v149, v149
	v_add_f32_e32 v149, 1.0, v150
	v_rcp_f32_e32 v150, v149
	v_add_f32_e32 v149, 1.0, v151
	v_rcp_f32_e32 v151, v149
	v_mul_f32_e32 v149, v126, v156
	v_exp_f32_e32 v149, v149
	v_add_f32_e32 v127, 1.0, v157
	v_rcp_f32_e32 v127, v127
	s_mul_hi_i32 s29, s11, 0x58
	v_add_f32_e32 v126, 1.0, v149
	v_rcp_f32_e32 v126, v126
	v_pk_mul_f32 v[124:125], v[148:149], v[150:151] op_sel_hi:[0,1]
	v_pk_mul_f32 v[120:121], v[120:121], v[124:125]
	s_add_u32 s28, s13, s2
	v_pk_mul_f32 v[124:125], v[148:149], v[126:127] op_sel_hi:[0,1]
	v_mul_f32_e32 v126, v116, v156
	v_mul_f32_e32 v127, v117, v156
	v_exp_f32_e32 v126, v126
	v_exp_f32_e32 v127, v127
	v_pk_mul_f32 v[122:123], v[122:123], v[124:125]
	v_pk_mul_f32 v[112:113], v[116:117], v[112:113]
	v_add_f32_e32 v124, 1.0, v126
	v_add_f32_e32 v125, 1.0, v127
	v_mul_f32_e32 v126, v118, v156
	v_mul_f32_e32 v127, v119, v156
	v_exp_f32_e32 v126, v126
	v_exp_f32_e32 v127, v127
	v_rcp_f32_e32 v124, v124
	v_rcp_f32_e32 v125, v125
	v_add_f32_e32 v118, 1.0, v126
	v_add_f32_e32 v119, 1.0, v127
	v_rcp_f32_e32 v118, v118
	v_rcp_f32_e32 v119, v119
	v_pk_mul_f32 v[116:117], v[148:149], v[124:125] op_sel_hi:[0,1]
	s_addc_u32 s29, s29, s3
	v_pk_mul_f32 v[116:117], v[112:113], v[116:117]
	v_pk_mul_f32 v[112:113], v[148:149], v[118:119] op_sel_hi:[0,1]
	s_lshl_b64 s[28:29], s[28:29], 10
	v_pk_mul_f32 v[118:119], v[114:115], v[112:113]
	v_lshl_add_u64 v[124:125], v[134:135], 0, s[28:29]
	v_cvt_pk_bf16_f32 v112, v120, v121
; __device__ __forceinline__ unsigned cvtpk(float lo, float hi) { f32x2_t v = {lo, hi}; bf16x2_t b = __builtin_convertvector(v, bf16x2_t); return __builtin_bit_cast(unsigned, b); }
;     __device__ __forceinline__ void operator()(const AccT& acc, const Unit& u, int wr, int wc, int fr, int fq, LAS unsigned char* stg) const {
;     ...
; #pragma unroll
;         for (int ai = 0; ai < 2; ++ai)
; #pragma unroll
;             for (int m = 0; m < 4; ++m) {
;                 bf16_t* rowp = O + ((size_t)(u.pm * 16 + wr * 4 + ai * 8 + m) * (ldo >> 5) + (u.pn * 4 + wc)) * 512 + fr * 32 + 8 * fq;
;                 const float k1 = rs[ai][m] * -1.4426950408889634f, k2 = rs[ai][m] * rs[ai][m];
;                 float r[8];
; #pragma unroll
;                 for (int n = 0; n < 2; ++n)
; #pragma unroll
;                     for (int i = 0; i < 4; ++i) {
;                         const float g = acc[ai][0][m][n][i], up = acc[ai][1][m][n][i];
;                         const float e = __builtin_amdgcn_exp2f(g * k1);
;                         r[n * 4 + i] = (g * up) * (k2 * __builtin_amdgcn_rcpf(1.0f + e));
;                     }
;                 u32x4 w; w.x = cvtpk(r[0], r[1]); w.y = cvtpk(r[2], r[3]); w.z = cvtpk(r[4], r[5]); w.w = cvtpk(r[6], r[7]);
;                 __builtin_nontemporal_store(w, (u32x4*)rowp);
;             }
	v_cvt_pk_bf16_f32 v113, v122, v123
	v_cvt_pk_bf16_f32 v114, v116, v117
	v_cvt_pk_bf16_f32 v115, v118, v119
	global_store_dwordx4 v[124:125], v[112:115], off nt
	v_pk_mul_f32 v[106:107], v[110:111], v[106:107]
	v_pk_mul_f32 v[104:105], v[108:109], v[104:105]
	v_mul_f32_e32 v113, 0xbfb8aa3b, v154
	v_mul_f32_e32 v112, v108, v113
	v_exp_f32_e32 v114, v112
	v_mul_f32_e32 v112, v109, v113
	v_exp_f32_e32 v115, v112
	v_mul_f32_e32 v116, v110, v113
	v_mul_f32_e32 v117, v111, v113
	v_exp_f32_e32 v116, v116
	v_exp_f32_e32 v117, v117
	v_add_f32_e32 v114, 1.0, v114
	v_add_f32_e32 v115, 1.0, v115
	v_rcp_f32_e32 v114, v114
	v_rcp_f32_e32 v115, v115
	v_add_f32_e32 v110, 1.0, v116
	v_add_f32_e32 v111, 1.0, v117
	v_rcp_f32_e32 v110, v110
	v_rcp_f32_e32 v111, v111
	v_mul_f32_e32 v112, v154, v154
	v_pk_mul_f32 v[108:109], v[112:113], v[114:115] op_sel_hi:[0,1]
	v_pk_mul_f32 v[104:105], v[104:105], v[108:109]
	v_pk_mul_f32 v[108:109], v[112:113], v[110:111] op_sel_hi:[0,1]
	v_mul_f32_e32 v110, v100, v113
	v_mul_f32_e32 v111, v101, v113
	v_exp_f32_e32 v110, v110
	v_exp_f32_e32 v111, v111
	v_pk_mul_f32 v[106:107], v[106:107], v[108:109]
	v_pk_mul_f32 v[98:99], v[102:103], v[98:99]
	v_add_f32_e32 v108, 1.0, v110
	v_add_f32_e32 v109, 1.0, v111
	v_mul_f32_e32 v110, v102, v113
	v_mul_f32_e32 v111, v103, v113
	v_exp_f32_e32 v110, v110
	v_exp_f32_e32 v111, v111
	v_rcp_f32_e32 v108, v108
	v_rcp_f32_e32 v109, v109
	v_add_f32_e32 v102, 1.0, v110
	v_add_f32_e32 v103, 1.0, v111
	v_rcp_f32_e32 v102, v102
	v_rcp_f32_e32 v103, v103
	s_or_b32 s28, s11, 1
	s_mul_hi_i32 s29, s28, 0x58
	s_mulk_i32 s28, 0x58
	s_add_u32 s28, s28, s2
	v_pk_mul_f32 v[96:97], v[100:101], v[96:97]
	v_pk_mul_f32 v[100:101], v[112:113], v[108:109] op_sel_hi:[0,1]
	s_addc_u32 s29, s29, s3
	v_pk_mul_f32 v[100:101], v[96:97], v[100:101]
	v_pk_mul_f32 v[96:97], v[112:113], v[102:103] op_sel_hi:[0,1]
	s_lshl_b64 s[28:29], s[28:29], 10
	v_pk_mul_f32 v[102:103], v[98:99], v[96:97]
	v_lshl_add_u64 v[108:109], v[134:135], 0, s[28:29]
	v_cvt_pk_bf16_f32 v96, v104, v105
	v_cvt_pk_bf16_f32 v97, v106, v107
	v_cvt_pk_bf16_f32 v98, v100, v101
	v_cvt_pk_bf16_f32 v99, v102, v103
	global_store_dwordx4 v[108:109], v[96:99], off nt
	v_pk_mul_f32 v[90:91], v[94:95], v[90:91]
	v_pk_mul_f32 v[88:89], v[92:93], v[88:89]
	v_mul_f32_e32 v97, 0xbfb8aa3b, v153
	v_mul_f32_e32 v96, v92, v97
	v_exp_f32_e32 v98, v96
	v_mul_f32_e32 v96, v93, v97
	v_exp_f32_e32 v99, v96
	v_mul_f32_e32 v100, v94, v97
	v_mul_f32_e32 v101, v95, v97
	v_exp_f32_e32 v100, v100
	v_exp_f32_e32 v101, v101
	v_add_f32_e32 v98, 1.0, v98
	v_add_f32_e32 v99, 1.0, v99
	v_rcp_f32_e32 v98, v98
	v_rcp_f32_e32 v99, v99
	v_add_f32_e32 v94, 1.0, v100
	v_add_f32_e32 v95, 1.0, v101
	v_rcp_f32_e32 v94, v94
	v_rcp_f32_e32 v95, v95
	v_mul_f32_e32 v96, v153, v153
	v_pk_mul_f32 v[92:93], v[96:97], v[98:99] op_sel_hi:[0,1]
	v_pk_mul_f32 v[88:89], v[88:89], v[92:93]
	v_pk_mul_f32 v[92:93], v[96:97], v[94:95] op_sel_hi:[0,1]
	v_mul_f32_e32 v94, v84, v97
	v_mul_f32_e32 v95, v85, v97
	v_exp_f32_e32 v94, v94
	v_exp_f32_e32 v95, v95
	v_pk_mul_f32 v[90:91], v[90:91], v[92:93]
	v_pk_mul_f32 v[82:83], v[86:87], v[82:83]
	v_add_f32_e32 v92, 1.0, v94
	v_add_f32_e32 v93, 1.0, v95
	v_mul_f32_e32 v94, v86, v97
	v_mul_f32_e32 v95, v87, v97
	v_exp_f32_e32 v94, v94
	v_exp_f32_e32 v95, v95
	v_rcp_f32_e32 v92, v92
	v_rcp_f32_e32 v93, v93
	v_add_f32_e32 v86, 1.0, v94
	v_add_f32_e32 v87, 1.0, v95
	v_rcp_f32_e32 v86, v86
	v_rcp_f32_e32 v87, v87
	s_or_b32 s28, s11, 2
	s_mul_hi_i32 s29, s28, 0x58
	s_mulk_i32 s28, 0x58
	s_add_u32 s28, s28, s2
	v_pk_mul_f32 v[80:81], v[84:85], v[80:81]
	v_pk_mul_f32 v[84:85], v[96:97], v[92:93] op_sel_hi:[0,1]
	s_addc_u32 s29, s29, s3
	v_pk_mul_f32 v[84:85], v[80:81], v[84:85]
	v_pk_mul_f32 v[80:81], v[96:97], v[86:87] op_sel_hi:[0,1]
	s_lshl_b64 s[28:29], s[28:29], 10
	v_pk_mul_f32 v[86:87], v[82:83], v[80:81]
	v_lshl_add_u64 v[92:93], v[134:135], 0, s[28:29]
	v_cvt_pk_bf16_f32 v80, v88, v89
	v_cvt_pk_bf16_f32 v81, v90, v91
	v_cvt_pk_bf16_f32 v82, v84, v85
	v_cvt_pk_bf16_f32 v83, v86, v87
	global_store_dwordx4 v[92:93], v[80:83], off nt
	v_pk_mul_f32 v[74:75], v[78:79], v[74:75]
	v_pk_mul_f32 v[72:73], v[76:77], v[72:73]
	v_mul_f32_e32 v81, 0xbfb8aa3b, v155
	v_mul_f32_e32 v80, v76, v81
	v_exp_f32_e32 v82, v80
	v_mul_f32_e32 v80, v77, v81
	v_exp_f32_e32 v83, v80
	v_mul_f32_e32 v84, v78, v81
	v_mul_f32_e32 v85, v79, v81
	v_exp_f32_e32 v84, v84
	v_exp_f32_e32 v85, v85
	v_add_f32_e32 v82, 1.0, v82
	v_add_f32_e32 v83, 1.0, v83
	v_rcp_f32_e32 v82, v82
	v_rcp_f32_e32 v83, v83
	v_add_f32_e32 v78, 1.0, v84
	v_add_f32_e32 v79, 1.0, v85
	v_rcp_f32_e32 v78, v78
	v_rcp_f32_e32 v79, v79
	v_mul_f32_e32 v80, v155, v155
	v_pk_mul_f32 v[76:77], v[80:81], v[82:83] op_sel_hi:[0,1]
	v_pk_mul_f32 v[72:73], v[72:73], v[76:77]
	v_pk_mul_f32 v[76:77], v[80:81], v[78:79] op_sel_hi:[0,1]
	v_mul_f32_e32 v78, v68, v81
	v_mul_f32_e32 v79, v69, v81
	v_exp_f32_e32 v78, v78
	v_exp_f32_e32 v79, v79
	v_pk_mul_f32 v[74:75], v[74:75], v[76:77]
	v_pk_mul_f32 v[66:67], v[70:71], v[66:67]
	v_add_f32_e32 v76, 1.0, v78
	v_add_f32_e32 v77, 1.0, v79
	v_mul_f32_e32 v78, v70, v81
	v_mul_f32_e32 v79, v71, v81
	v_exp_f32_e32 v78, v78
	v_exp_f32_e32 v79, v79
	v_rcp_f32_e32 v76, v76
	v_rcp_f32_e32 v77, v77
	v_add_f32_e32 v70, 1.0, v78
	v_add_f32_e32 v71, 1.0, v79
	v_rcp_f32_e32 v70, v70
	v_rcp_f32_e32 v71, v71
	s_or_b32 s28, s11, 3
	s_mul_hi_i32 s29, s28, 0x58
	s_mulk_i32 s28, 0x58
	s_add_u32 s28, s28, s2
	v_pk_mul_f32 v[64:65], v[68:69], v[64:65]
	v_pk_mul_f32 v[68:69], v[80:81], v[76:77] op_sel_hi:[0,1]
	s_addc_u32 s29, s29, s3
	v_pk_mul_f32 v[68:69], v[64:65], v[68:69]
	v_pk_mul_f32 v[64:65], v[80:81], v[70:71] op_sel_hi:[0,1]
; __device__ __forceinline__ unsigned cvtpk(float lo, float hi) { f32x2_t v = {lo, hi}; bf16x2_t b = __builtin_convertvector(v, bf16x2_t); return __builtin_bit_cast(unsigned, b); }
;     __device__ __forceinline__ void operator()(const AccT& acc, const Unit& u, int wr, int wc, int fr, int fq, LAS unsigned char* stg) const {
;     ...
; #pragma unroll
;         for (int ai = 0; ai < 2; ++ai)
; #pragma unroll
;             for (int m = 0; m < 4; ++m) {
;                 bf16_t* rowp = O + ((size_t)(u.pm * 16 + wr * 4 + ai * 8 + m) * (ldo >> 5) + (u.pn * 4 + wc)) * 512 + fr * 32 + 8 * fq;
;                 const float k1 = rs[ai][m] * -1.4426950408889634f, k2 = rs[ai][m] * rs[ai][m];
;                 float r[8];
; #pragma unroll
;                 for (int n = 0; n < 2; ++n)
; #pragma unroll
;                     for (int i = 0; i < 4; ++i) {
;                         const float g = acc[ai][0][m][n][i], up = acc[ai][1][m][n][i];
;                         const float e = __builtin_amdgcn_exp2f(g * k1);
;                         r[n * 4 + i] = (g * up) * (k2 * __builtin_amdgcn_rcpf(1.0f + e));
;                     }
;                 u32x4 w; w.x = cvtpk(r[0], r[1]); w.y = cvtpk(r[2], r[3]); w.z = cvtpk(r[4], r[5]); w.w = cvtpk(r[6], r[7]);
;                 __builtin_nontemporal_store(w, (u32x4*)rowp);
;             }
	s_lshl_b64 s[28:29], s[28:29], 10
	v_pk_mul_f32 v[70:71], v[66:67], v[64:65]
	v_lshl_add_u64 v[76:77], v[134:135], 0, s[28:29]
	v_cvt_pk_bf16_f32 v64, v72, v73
	v_cvt_pk_bf16_f32 v65, v74, v75
	v_cvt_pk_bf16_f32 v66, v68, v69
	v_cvt_pk_bf16_f32 v67, v70, v71
	global_store_dwordx4 v[76:77], v[64:67], off nt
	v_pk_mul_f32 v[58:59], v[62:63], v[58:59]
	v_pk_mul_f32 v[56:57], v[60:61], v[56:57]
	v_mul_f32_e32 v65, 0xbfb8aa3b, v152
	v_mul_f32_e32 v64, v60, v65
	v_exp_f32_e32 v66, v64
	v_mul_f32_e32 v64, v61, v65
	v_exp_f32_e32 v67, v64
	v_mul_f32_e32 v68, v62, v65
	v_mul_f32_e32 v69, v63, v65
	v_exp_f32_e32 v68, v68
	v_exp_f32_e32 v69, v69
	v_add_f32_e32 v66, 1.0, v66
	v_add_f32_e32 v67, 1.0, v67
	v_rcp_f32_e32 v66, v66
	v_rcp_f32_e32 v67, v67
	v_add_f32_e32 v62, 1.0, v68
	v_add_f32_e32 v63, 1.0, v69
	v_rcp_f32_e32 v62, v62
	v_rcp_f32_e32 v63, v63
	v_mul_f32_e32 v64, v152, v152
	v_pk_mul_f32 v[60:61], v[64:65], v[66:67] op_sel_hi:[0,1]
	v_pk_mul_f32 v[56:57], v[56:57], v[60:61]
	v_pk_mul_f32 v[60:61], v[64:65], v[62:63] op_sel_hi:[0,1]
	v_mul_f32_e32 v62, v52, v65
	v_mul_f32_e32 v63, v53, v65
	v_exp_f32_e32 v62, v62
	v_exp_f32_e32 v63, v63
	v_pk_mul_f32 v[58:59], v[58:59], v[60:61]
	v_pk_mul_f32 v[50:51], v[54:55], v[50:51]
	v_add_f32_e32 v60, 1.0, v62
	v_add_f32_e32 v61, 1.0, v63
	v_mul_f32_e32 v62, v54, v65
	v_mul_f32_e32 v63, v55, v65
	v_exp_f32_e32 v62, v62
	v_exp_f32_e32 v63, v63
	v_rcp_f32_e32 v60, v60
	v_rcp_f32_e32 v61, v61
	v_add_f32_e32 v54, 1.0, v62
	v_add_f32_e32 v55, 1.0, v63
	v_rcp_f32_e32 v54, v54
	v_rcp_f32_e32 v55, v55
	s_add_i32 s28, s11, 8
	v_fmamk_f32 v147, v147, 0x3a800000, v220
	s_mul_hi_i32 s29, s28, 0x58
	s_add_i32 s28, s13, 0x2c0
	v_rsq_f32_e32 v147, v147
	s_add_u32 s28, s28, s2
	v_pk_mul_f32 v[48:49], v[52:53], v[48:49]
	v_pk_mul_f32 v[52:53], v[64:65], v[60:61] op_sel_hi:[0,1]
	s_addc_u32 s29, s29, s3
	v_pk_mul_f32 v[52:53], v[48:49], v[52:53]
	v_pk_mul_f32 v[48:49], v[64:65], v[54:55] op_sel_hi:[0,1]
	s_lshl_b64 s[28:29], s[28:29], 10
	v_pk_mul_f32 v[54:55], v[50:51], v[48:49]
	v_lshl_add_u64 v[60:61], v[134:135], 0, s[28:29]
	v_cvt_pk_bf16_f32 v48, v56, v57
	v_cvt_pk_bf16_f32 v49, v58, v59
	v_cvt_pk_bf16_f32 v50, v52, v53
	v_cvt_pk_bf16_f32 v51, v54, v55
	global_store_dwordx4 v[60:61], v[48:51], off nt
	v_pk_mul_f32 v[42:43], v[46:47], v[42:43]
	v_pk_mul_f32 v[40:41], v[44:45], v[40:41]
	v_mul_f32_e32 v49, 0xbfb8aa3b, v147
	v_mul_f32_e32 v48, v44, v49
	v_exp_f32_e32 v50, v48
	v_mul_f32_e32 v48, v45, v49
	v_exp_f32_e32 v51, v48
	v_mul_f32_e32 v52, v46, v49
	v_mul_f32_e32 v53, v47, v49
	v_exp_f32_e32 v52, v52
	v_exp_f32_e32 v53, v53
	v_add_f32_e32 v50, 1.0, v50
	v_add_f32_e32 v51, 1.0, v51
	v_rcp_f32_e32 v50, v50
	v_rcp_f32_e32 v51, v51
	v_add_f32_e32 v46, 1.0, v52
	v_add_f32_e32 v47, 1.0, v53
	v_rcp_f32_e32 v46, v46
	v_rcp_f32_e32 v47, v47
	v_mul_f32_e32 v48, v147, v147
	v_pk_mul_f32 v[44:45], v[48:49], v[50:51] op_sel_hi:[0,1]
	v_pk_mul_f32 v[40:41], v[40:41], v[44:45]
	v_pk_mul_f32 v[44:45], v[48:49], v[46:47] op_sel_hi:[0,1]
	v_mul_f32_e32 v46, v36, v49
	v_mul_f32_e32 v47, v37, v49
	v_exp_f32_e32 v46, v46
	v_exp_f32_e32 v47, v47
	v_pk_mul_f32 v[42:43], v[42:43], v[44:45]
	v_pk_mul_f32 v[34:35], v[38:39], v[34:35]
	v_add_f32_e32 v44, 1.0, v46
	v_add_f32_e32 v45, 1.0, v47
	v_mul_f32_e32 v46, v38, v49
	v_mul_f32_e32 v47, v39, v49
	v_exp_f32_e32 v46, v46
	v_exp_f32_e32 v47, v47
	v_rcp_f32_e32 v44, v44
	v_rcp_f32_e32 v45, v45
	v_add_f32_e32 v38, 1.0, v46
	v_add_f32_e32 v39, 1.0, v47
	v_rcp_f32_e32 v38, v38
	v_rcp_f32_e32 v39, v39
	s_add_i32 s28, s11, 9
	v_fmamk_f32 v146, v146, 0x3a800000, v220
	s_mul_hi_i32 s29, s28, 0x58
	s_add_i32 s28, s13, 0x318
	v_rsq_f32_e32 v146, v146
	s_add_u32 s28, s28, s2
	v_pk_mul_f32 v[32:33], v[36:37], v[32:33]
	v_pk_mul_f32 v[36:37], v[48:49], v[44:45] op_sel_hi:[0,1]
	s_addc_u32 s29, s29, s3
	v_pk_mul_f32 v[36:37], v[32:33], v[36:37]
	v_pk_mul_f32 v[32:33], v[48:49], v[38:39] op_sel_hi:[0,1]
	s_lshl_b64 s[28:29], s[28:29], 10
	v_pk_mul_f32 v[38:39], v[34:35], v[32:33]
	v_lshl_add_u64 v[44:45], v[134:135], 0, s[28:29]
	v_cvt_pk_bf16_f32 v32, v40, v41
; __device__ __forceinline__ unsigned cvtpk(float lo, float hi) { f32x2_t v = {lo, hi}; bf16x2_t b = __builtin_convertvector(v, bf16x2_t); return __builtin_bit_cast(unsigned, b); }
;     __device__ __forceinline__ void operator()(const AccT& acc, const Unit& u, int wr, int wc, int fr, int fq, LAS unsigned char* stg) const {
;     ...
; #pragma unroll
;         for (int ai = 0; ai < 2; ++ai)
; #pragma unroll
;             for (int m = 0; m < 4; ++m) {
;                 bf16_t* rowp = O + ((size_t)(u.pm * 16 + wr * 4 + ai * 8 + m) * (ldo >> 5) + (u.pn * 4 + wc)) * 512 + fr * 32 + 8 * fq;
;                 const float k1 = rs[ai][m] * -1.4426950408889634f, k2 = rs[ai][m] * rs[ai][m];
;                 float r[8];
; #pragma unroll
;                 for (int n = 0; n < 2; ++n)
; #pragma unroll
;                     for (int i = 0; i < 4; ++i) {
;                         const float g = acc[ai][0][m][n][i], up = acc[ai][1][m][n][i];
;                         const float e = __builtin_amdgcn_exp2f(g * k1);
;                         r[n * 4 + i] = (g * up) * (k2 * __builtin_amdgcn_rcpf(1.0f + e));
;                     }
;                 u32x4 w; w.x = cvtpk(r[0], r[1]); w.y = cvtpk(r[2], r[3]); w.z = cvtpk(r[4], r[5]); w.w = cvtpk(r[6], r[7]);
;                 __builtin_nontemporal_store(w, (u32x4*)rowp);
;             }
	v_cvt_pk_bf16_f32 v33, v42, v43
	v_cvt_pk_bf16_f32 v34, v36, v37
	v_cvt_pk_bf16_f32 v35, v38, v39
	global_store_dwordx4 v[44:45], v[32:35], off nt
	v_pk_mul_f32 v[26:27], v[30:31], v[26:27]
	v_pk_mul_f32 v[24:25], v[28:29], v[24:25]
	v_mul_f32_e32 v33, 0xbfb8aa3b, v146
	v_mul_f32_e32 v32, v28, v33
	v_exp_f32_e32 v34, v32
	v_mul_f32_e32 v32, v29, v33
	v_exp_f32_e32 v35, v32
	v_mul_f32_e32 v36, v30, v33
	v_mul_f32_e32 v37, v31, v33
	v_exp_f32_e32 v36, v36
	v_exp_f32_e32 v37, v37
	v_add_f32_e32 v34, 1.0, v34
	v_add_f32_e32 v35, 1.0, v35
	v_rcp_f32_e32 v34, v34
	v_rcp_f32_e32 v35, v35
	v_add_f32_e32 v30, 1.0, v36
	v_add_f32_e32 v31, 1.0, v37
	v_rcp_f32_e32 v30, v30
	v_rcp_f32_e32 v31, v31
	v_mul_f32_e32 v32, v146, v146
	v_pk_mul_f32 v[28:29], v[32:33], v[34:35] op_sel_hi:[0,1]
	v_pk_mul_f32 v[24:25], v[24:25], v[28:29]
	v_pk_mul_f32 v[28:29], v[32:33], v[30:31] op_sel_hi:[0,1]
	v_mul_f32_e32 v30, v20, v33
	v_mul_f32_e32 v31, v21, v33
	v_exp_f32_e32 v30, v30
	v_exp_f32_e32 v31, v31
	v_pk_mul_f32 v[26:27], v[26:27], v[28:29]
	v_pk_mul_f32 v[18:19], v[22:23], v[18:19]
	v_add_f32_e32 v28, 1.0, v30
	v_add_f32_e32 v29, 1.0, v31
	v_mul_f32_e32 v30, v22, v33
	v_mul_f32_e32 v31, v23, v33
	v_exp_f32_e32 v30, v30
	v_exp_f32_e32 v31, v31
	v_rcp_f32_e32 v28, v28
	v_rcp_f32_e32 v29, v29
	v_add_f32_e32 v22, 1.0, v30
	v_add_f32_e32 v23, 1.0, v31
	v_rcp_f32_e32 v22, v22
	v_rcp_f32_e32 v23, v23
	s_add_i32 s28, s11, 10
	v_fmamk_f32 v145, v145, 0x3a800000, v220
	s_mul_hi_i32 s29, s28, 0x58
	s_add_i32 s28, s13, 0x370
	v_rsq_f32_e32 v145, v145
	s_add_u32 s28, s28, s2
	v_pk_mul_f32 v[16:17], v[20:21], v[16:17]
	v_pk_mul_f32 v[20:21], v[32:33], v[28:29] op_sel_hi:[0,1]
	s_addc_u32 s29, s29, s3
	v_pk_mul_f32 v[20:21], v[16:17], v[20:21]
	v_pk_mul_f32 v[16:17], v[32:33], v[22:23] op_sel_hi:[0,1]
	s_lshl_b64 s[28:29], s[28:29], 10
	v_pk_mul_f32 v[22:23], v[18:19], v[16:17]
	v_lshl_add_u64 v[28:29], v[134:135], 0, s[28:29]
	v_cvt_pk_bf16_f32 v16, v24, v25
	v_cvt_pk_bf16_f32 v17, v26, v27
	v_cvt_pk_bf16_f32 v18, v20, v21
	v_cvt_pk_bf16_f32 v19, v22, v23
	global_store_dwordx4 v[28:29], v[16:19], off nt
	v_pk_mul_f32 v[10:11], v[14:15], v[10:11]
	v_pk_mul_f32 v[8:9], v[12:13], v[8:9]
	v_mul_f32_e32 v17, 0xbfb8aa3b, v145
	v_mul_f32_e32 v16, v12, v17
	v_exp_f32_e32 v18, v16
	v_mul_f32_e32 v16, v13, v17
	v_exp_f32_e32 v19, v16
	v_mul_f32_e32 v20, v14, v17
	v_mul_f32_e32 v21, v15, v17
	v_exp_f32_e32 v20, v20
	v_exp_f32_e32 v21, v21
	v_add_f32_e32 v18, 1.0, v18
	v_add_f32_e32 v19, 1.0, v19
	v_rcp_f32_e32 v18, v18
	v_rcp_f32_e32 v19, v19
	v_add_f32_e32 v14, 1.0, v20
	v_add_f32_e32 v15, 1.0, v21
	v_rcp_f32_e32 v14, v14
	v_rcp_f32_e32 v15, v15
	v_mul_f32_e32 v16, v145, v145
	v_pk_mul_f32 v[12:13], v[16:17], v[18:19] op_sel_hi:[0,1]
	v_pk_mul_f32 v[8:9], v[8:9], v[12:13]
	v_pk_mul_f32 v[12:13], v[16:17], v[14:15] op_sel_hi:[0,1]
	v_mul_f32_e32 v14, v4, v17
	v_mul_f32_e32 v15, v5, v17
	v_exp_f32_e32 v14, v14
	v_exp_f32_e32 v15, v15
	v_pk_mul_f32 v[10:11], v[10:11], v[12:13]
	v_pk_mul_f32 v[2:3], v[6:7], v[2:3]
	v_add_f32_e32 v12, 1.0, v14
	v_add_f32_e32 v13, 1.0, v15
	v_mul_f32_e32 v14, v6, v17
	v_mul_f32_e32 v15, v7, v17
	v_exp_f32_e32 v14, v14
	v_exp_f32_e32 v15, v15
	v_rcp_f32_e32 v12, v12
	v_rcp_f32_e32 v13, v13
	v_add_f32_e32 v6, 1.0, v14
	v_add_f32_e32 v7, 1.0, v15
	v_rcp_f32_e32 v6, v6
	v_rcp_f32_e32 v7, v7
	s_add_i32 s11, s11, 11
	s_addk_i32 s13, 0x3c8
	s_mul_hi_i32 s11, s11, 0x58
	s_add_u32 s2, s13, s2
	v_pk_mul_f32 v[0:1], v[4:5], v[0:1]
	v_pk_mul_f32 v[4:5], v[16:17], v[12:13] op_sel_hi:[0,1]
	s_addc_u32 s3, s11, s3
	v_pk_mul_f32 v[4:5], v[0:1], v[4:5]
	v_pk_mul_f32 v[0:1], v[16:17], v[6:7] op_sel_hi:[0,1]
	s_lshl_b64 s[2:3], s[2:3], 10
	v_pk_mul_f32 v[6:7], v[2:3], v[0:1]
	v_lshl_add_u64 v[12:13], v[134:135], 0, s[2:3]
	v_cvt_pk_bf16_f32 v0, v8, v9
	v_cvt_pk_bf16_f32 v1, v10, v11
	v_cvt_pk_bf16_f32 v2, v4, v5
	v_cvt_pk_bf16_f32 v3, v6, v7
	s_andn2_b64 vcc, exec, s[4:5]
	s_mov_b64 s[2:3], -1
	global_store_dwordx4 v[12:13], v[0:3], off nt
	s_cbranch_vccnz .LBB0_449
	s_andn2_b64 vcc, exec, s[6:7]
	s_cbranch_vccnz .LBB0_448
	s_barrier
	s_branch .LBB0_448

; __global__ void __launch_bounds__(512, 2) mk_fwd(Args args) {
	.amdhsa_kernel _Z6mk_fwd4Args
		.amdhsa_group_segment_fixed_size 0
		.amdhsa_private_segment_fixed_size 0
		.amdhsa_kernarg_size 456
		.amdhsa_user_sgpr_count 2
		.amdhsa_user_sgpr_dispatch_ptr 0
		.amdhsa_user_sgpr_queue_ptr 0
		.amdhsa_user_sgpr_kernarg_segment_ptr 1
		.amdhsa_user_sgpr_dispatch_id 0
		.amdhsa_user_sgpr_kernarg_preload_length 0
		.amdhsa_user_sgpr_kernarg_preload_offset 0
		.amdhsa_user_sgpr_private_segment_size 0
		.amdhsa_uses_dynamic_stack 0
		.amdhsa_enable_private_segment 0
		.amdhsa_system_sgpr_workgroup_id_x 1
		.amdhsa_system_sgpr_workgroup_id_y 0
		.amdhsa_system_sgpr_workgroup_id_z 0
		.amdhsa_system_sgpr_workgroup_info 0
		.amdhsa_system_vgpr_workitem_id 2
		.amdhsa_next_free_vgpr 256
		.amdhsa_next_free_sgpr 102
		.amdhsa_accum_offset 256
		.amdhsa_reserve_vcc 1
		.amdhsa_float_round_mode_32 0
		.amdhsa_float_round_mode_16_64 0
		.amdhsa_float_denorm_mode_32 3
		.amdhsa_float_denorm_mode_16_64 3
		.amdhsa_dx10_clamp 1
		.amdhsa_ieee_mode 1
		.amdhsa_fp16_overflow 0
		.amdhsa_tg_split 0
		.amdhsa_exception_fp_ieee_invalid_op 0
		.amdhsa_exception_fp_denorm_src 0
		.amdhsa_exception_fp_ieee_div_zero 0
		.amdhsa_exception_fp_ieee_overflow 0
		.amdhsa_exception_fp_ieee_underflow 0
		.amdhsa_exception_fp_ieee_inexact 0
		.amdhsa_exception_int_div_zero 0
	.end_amdhsa_kernel

; __global__ void __launch_bounds__(512, 2) mk_fwd(Args args) {
amdhsa.kernels:
  - .agpr_count:     0
    .args:
      - .offset:         0
        .size:           200
        .value_kind:     by_value
      - .offset:         200
        .size:           4
        .value_kind:     hidden_block_count_x
      - .offset:         204
        .size:           4
        .value_kind:     hidden_block_count_y
      - .offset:         208
        .size:           4
        .value_kind:     hidden_block_count_z
      - .offset:         212
        .size:           2
        .value_kind:     hidden_group_size_x
      - .offset:         214
        .size:           2
        .value_kind:     hidden_group_size_y
      - .offset:         216
        .size:           2
        .value_kind:     hidden_group_size_z
      - .offset:         218
        .size:           2
        .value_kind:     hidden_remainder_x
      - .offset:         220
        .size:           2
        .value_kind:     hidden_remainder_y
      - .offset:         222
        .size:           2
        .value_kind:     hidden_remainder_z
      - .offset:         240
        .size:           8
        .value_kind:     hidden_global_offset_x
      - .offset:         248
        .size:           8
        .value_kind:     hidden_global_offset_y
      - .offset:         256
        .size:           8
        .value_kind:     hidden_global_offset_z
      - .offset:         264
        .size:           2
        .value_kind:     hidden_grid_dims
      - .offset:         288
        .size:           8
        .value_kind:     hidden_multigrid_sync_arg
      - .offset:         320
        .size:           4
        .value_kind:     hidden_dynamic_lds_size
    .group_segment_fixed_size: 0
    .kernarg_segment_align: 8
    .kernarg_segment_size: 456
    .language:       OpenCL C
    .language_version:
      - 2
      - 0
    .max_flat_workgroup_size: 512
    .name:           _Z6mk_fwd4Args
    .private_segment_fixed_size: 0
    .sgpr_count:     108
    .sgpr_spill_count: 208
    .symbol:         _Z6mk_fwd4Args.kd
    .uniform_work_group_size: 1
    .uses_dynamic_stack: false
    .vgpr_count:     256
    .vgpr_spill_count: 0
    .wavefront_size: 64
